# EpiRes2 row sum-of-squares cross-row reduction via permlane16/32 swap instead of ds_bpermute (32 pairs in Out0/Dn0/Out1/Dn1 epilogues)
# speedup vs baseline: 1.0075x; 1.0075x over previous
; DI unsigned pk_bf16(float a, float b) { f32x2 v = {a, b}; bf2_t r = __builtin_convertvector(v, bf2_t); return __builtin_bit_cast(unsigned, r); }
;     DI void operator()(const pg8::f32x4 (&acc)[2][2][4][2], const pg8::Unit& u, int wr, int wc, int fr, int fq) const {
;     ...
;                 const int row = row0 + ai * 128 + m * 16; float ss = 0.f;
;                 const float r2 = sumsq_in ? 1.0f / (sumsq_in[row] * (1.0f / 1024.0f) + EPS) : 1.0f;
; #pragma unroll
;                 for (int bj = 0; bj < 2; ++bj) {
;                     const size_t off = (size_t)row * 1024 + col0 + bj * 128;
;                     f32x4 r0 = *(const f32x4*)(resid + off), r1 = *(const f32x4*)(resid + off + 4);
; #pragma unroll
;                     for (int e = 0; e < 4; ++e) { r0[e] += acc[ai][bj][m][0][e] * r2; r1[e] += acc[ai][bj][m][1][e] * r2; ss += r0[e] * r0[e] + r1[e] * r1[e]; }
;                     *(f32x4*)(hout + off) = r0; *(f32x4*)(hout + off + 4) = r1;
;                     u32x4 w; w.x = pk_bf16(r0[0], r0[1]); w.y = pk_bf16(r0[2], r0[3]); w.z = pk_bf16(r1[0], r1[1]); w.w = pk_bf16(r1[2], r1[3]);
;                     if (hb) *(u32x4*)(hb + off) = w;
;                 }
;                 ss += __shfl_xor(ss, 16); ss += __shfl_xor(ss, 32);
;                 if (fq == 0) __hip_atomic_fetch_add(sumsq_next + row, ss, __ATOMIC_RELAXED, __HIP_MEMORY_SCOPE_AGENT);
;                 asm volatile("" ::: "memory");
.LBB0_1425:
	v_lshl_add_u32 v148, s28, 8, v1
	v_lshl_or_b32 v146, s30, 8, v151
	v_ashrrev_i32_e32 v149, 31, v148
	v_ashrrev_i32_e32 v147, 31, v146
	v_lshlrev_b64 v[156:157], 10, v[148:149]
	v_lshl_add_u64 v[164:165], v[156:157], 0, v[146:147]
	v_lshlrev_b64 v[166:167], 2, v[164:165]
	v_lshl_add_u64 v[168:169], s[8:9], 0, v[166:167]
	global_load_dwordx4 v[156:159], v[168:169], off
	global_load_dwordx4 v[160:163], v[168:169], off offset:16
	v_lshlrev_b64 v[170:171], 1, v[164:165]
	v_lshl_add_u64 v[172:173], s[10:11], 0, v[166:167]
	v_lshl_add_u64 v[164:165], s[64:65], 0, v[170:171]
	v_or_b32_e32 v170, 0x100, v170
	s_waitcnt vmcnt(0)
	v_pk_add_f32 v[128:129], v[128:129], v[158:159]
	v_pk_add_f32 v[126:127], v[126:127], v[156:157]
	v_pk_add_f32 v[158:159], v[124:125], v[162:163]
	v_pk_add_f32 v[156:157], v[122:123], v[160:161]
	v_cvt_pk_bf16_f32 v122, v126, v127
	v_cvt_pk_bf16_f32 v123, v128, v129
	v_cvt_pk_bf16_f32 v124, v156, v157
	v_cvt_pk_bf16_f32 v125, v158, v159
	global_store_dwordx4 v[172:173], v[126:129], off
	global_store_dwordx4 v[172:173], v[156:159], off offset:16
	global_store_dwordx4 v[164:165], v[122:125], off
	global_load_dwordx4 v[160:163], v[168:169], off offset:512
	s_nop 0
	global_load_dwordx4 v[164:167], v[168:169], off offset:528
	v_and_b32_e32 v123, 64, v155
	v_xor_b32_e32 v122, 16, v155
	v_add_u32_e32 v123, 64, v123
	v_xor_b32_e32 v124, 32, v155
	v_cmp_lt_i32_e32 vcc, v122, v123
	v_pk_mul_f32 v[156:157], v[156:157], v[156:157]
	s_waitcnt vmcnt(1)
	v_pk_add_f32 v[118:119], v[118:119], v[160:161]
	v_cndmask_b32_e32 v122, v155, v122, vcc
	v_cmp_lt_i32_e32 vcc, v124, v123
	v_lshlrev_b32_e32 v123, 2, v122
	v_pk_fma_f32 v[126:127], v[126:127], v[126:127], v[156:157]
	v_cndmask_b32_e32 v124, v155, v124, vcc
	v_lshlrev_b32_e32 v122, 2, v124
	v_pk_mul_f32 v[124:125], v[158:159], v[158:159]
	v_add_f32_e32 v126, v126, v127
	v_pk_fma_f32 v[124:125], v[128:129], v[128:129], v[124:125]
	v_pk_add_f32 v[120:121], v[120:121], v[162:163]
	v_add_f32_e32 v124, v124, v126
	v_add_f32_e32 v128, v125, v124
	s_waitcnt vmcnt(0)
	v_pk_add_f32 v[124:125], v[114:115], v[164:165]
	v_pk_add_f32 v[126:127], v[116:117], v[166:167]
	v_pk_mul_f32 v[116:117], v[124:125], v[124:125]
	v_pk_mul_f32 v[114:115], v[126:127], v[126:127]
	v_pk_fma_f32 v[116:117], v[118:119], v[118:119], v[116:117]
	v_pk_fma_f32 v[114:115], v[120:121], v[120:121], v[114:115]
	v_add_f32_e32 v116, v128, v116
	v_add_f32_e32 v116, v117, v116
	v_add_f32_e32 v114, v114, v116
	v_add_f32_e32 v114, v115, v114
	v_mov_b32_e32 v115, v114
	s_nop 1
	v_permlane16_swap_b32_e32 v114, v115
	global_store_dwordx4 v[172:173], v[118:121], off offset:512
	v_lshl_add_u64 v[128:129], s[64:65], 0, v[170:171]
	v_cvt_pk_bf16_f32 v116, v118, v119
	v_cvt_pk_bf16_f32 v117, v120, v121
	s_waitcnt lgkmcnt(0)
	v_add_f32_e32 v114, v114, v115
	v_mov_b32_e32 v115, v114
	s_nop 1
	v_permlane32_swap_b32_e32 v114, v115
	v_cvt_pk_bf16_f32 v118, v124, v125
	v_cvt_pk_bf16_f32 v119, v126, v127
	global_store_dwordx4 v[172:173], v[124:127], off offset:528
	global_store_dwordx4 v[128:129], v[116:119], off
	s_and_saveexec_b64 s[28:29], s[2:3]
	s_cbranch_execz .LBB0_1427
	v_lshl_add_u64 v[116:117], v[148:149], 2, s[14:15]
	s_waitcnt lgkmcnt(0)
	v_add_f32_e32 v114, v114, v115
	global_atomic_add_f32 v[116:117], v114, off
.LBB0_1427:
	s_or_b64 exec, exec, s[28:29]
	v_or_b32_e32 v114, 16, v148
	s_waitcnt lgkmcnt(0)
	v_ashrrev_i32_e32 v115, 31, v114
	v_lshlrev_b64 v[116:117], 10, v[114:115]
	v_lshl_add_u64 v[120:121], v[116:117], 0, v[146:147]
	v_lshlrev_b64 v[128:129], 2, v[120:121]
	v_lshl_add_u64 v[156:157], s[8:9], 0, v[128:129]
	global_load_dwordx4 v[116:119], v[156:157], off
	global_load_dwordx4 v[124:127], v[156:157], off offset:16
	v_lshlrev_b64 v[120:121], 1, v[120:121]
	v_lshl_add_u64 v[128:129], s[10:11], 0, v[128:129]
	v_lshl_add_u64 v[158:159], s[64:65], 0, v[120:121]
	v_or_b32_e32 v120, 0x100, v120
	s_waitcnt vmcnt(1)
	v_pk_add_f32 v[112:113], v[112:113], v[118:119]
	v_pk_add_f32 v[110:111], v[110:111], v[116:117]
	s_waitcnt vmcnt(0)
	v_pk_add_f32 v[108:109], v[108:109], v[126:127]
	v_pk_add_f32 v[106:107], v[106:107], v[124:125]
	v_cvt_pk_bf16_f32 v116, v110, v111
	v_cvt_pk_bf16_f32 v117, v112, v113
	v_cvt_pk_bf16_f32 v118, v106, v107
	v_cvt_pk_bf16_f32 v119, v108, v109
	global_store_dwordx4 v[128:129], v[110:113], off
	global_store_dwordx4 v[128:129], v[106:109], off offset:16
	global_store_dwordx4 v[158:159], v[116:119], off
	global_load_dwordx4 v[116:119], v[156:157], off offset:512
	s_nop 0
	global_load_dwordx4 v[124:127], v[156:157], off offset:528
	v_pk_mul_f32 v[106:107], v[106:107], v[106:107]
	v_pk_mul_f32 v[108:109], v[108:109], v[108:109]
	v_pk_fma_f32 v[106:107], v[110:111], v[110:111], v[106:107]
	v_pk_fma_f32 v[108:109], v[112:113], v[112:113], v[108:109]
	v_add_f32_e32 v106, v106, v107
	v_add_f32_e32 v106, v108, v106
	v_add_f32_e32 v110, v109, v106
	s_waitcnt vmcnt(1)
	v_pk_add_f32 v[102:103], v[102:103], v[116:117]
	s_waitcnt vmcnt(0)
	v_pk_add_f32 v[106:107], v[98:99], v[124:125]
	v_pk_add_f32 v[108:109], v[100:101], v[126:127]
	v_pk_mul_f32 v[100:101], v[106:107], v[106:107]
	v_pk_add_f32 v[104:105], v[104:105], v[118:119]
	v_pk_fma_f32 v[100:101], v[102:103], v[102:103], v[100:101]
	v_pk_mul_f32 v[98:99], v[108:109], v[108:109]
	v_add_f32_e32 v100, v110, v100
	v_pk_fma_f32 v[98:99], v[104:105], v[104:105], v[98:99]
	v_add_f32_e32 v100, v101, v100
	v_add_f32_e32 v98, v98, v100
	v_add_f32_e32 v98, v99, v98
	v_mov_b32_e32 v99, v98
	s_nop 1
	v_permlane16_swap_b32_e32 v98, v99
	global_store_dwordx4 v[128:129], v[102:105], off offset:512
	v_lshl_add_u64 v[110:111], s[64:65], 0, v[120:121]
	v_cvt_pk_bf16_f32 v100, v102, v103
	v_cvt_pk_bf16_f32 v101, v104, v105
	s_waitcnt lgkmcnt(0)
	v_add_f32_e32 v98, v98, v99
	v_mov_b32_e32 v99, v98
	s_nop 1
	v_permlane32_swap_b32_e32 v98, v99
	v_cvt_pk_bf16_f32 v102, v106, v107
	v_cvt_pk_bf16_f32 v103, v108, v109
	global_store_dwordx4 v[128:129], v[106:109], off offset:528
	global_store_dwordx4 v[110:111], v[100:103], off
	s_and_saveexec_b64 s[28:29], s[2:3]
	s_cbranch_execz .LBB0_1429
	v_lshl_add_u64 v[100:101], v[114:115], 2, s[14:15]
	s_waitcnt lgkmcnt(0)
	v_add_f32_e32 v98, v98, v99
	global_atomic_add_f32 v[100:101], v98, off
; DI unsigned pk_bf16(float a, float b) { f32x2 v = {a, b}; bf2_t r = __builtin_convertvector(v, bf2_t); return __builtin_bit_cast(unsigned, r); }
;     DI void operator()(const pg8::f32x4 (&acc)[2][2][4][2], const pg8::Unit& u, int wr, int wc, int fr, int fq) const {
;     ...
;                 const int row = row0 + ai * 128 + m * 16; float ss = 0.f;
;                 const float r2 = sumsq_in ? 1.0f / (sumsq_in[row] * (1.0f / 1024.0f) + EPS) : 1.0f;
; #pragma unroll
;                 for (int bj = 0; bj < 2; ++bj) {
;                     const size_t off = (size_t)row * 1024 + col0 + bj * 128;
;                     f32x4 r0 = *(const f32x4*)(resid + off), r1 = *(const f32x4*)(resid + off + 4);
; #pragma unroll
;                     for (int e = 0; e < 4; ++e) { r0[e] += acc[ai][bj][m][0][e] * r2; r1[e] += acc[ai][bj][m][1][e] * r2; ss += r0[e] * r0[e] + r1[e] * r1[e]; }
;                     *(f32x4*)(hout + off) = r0; *(f32x4*)(hout + off + 4) = r1;
;                     u32x4 w; w.x = pk_bf16(r0[0], r0[1]); w.y = pk_bf16(r0[2], r0[3]); w.z = pk_bf16(r1[0], r1[1]); w.w = pk_bf16(r1[2], r1[3]);
;                     if (hb) *(u32x4*)(hb + off) = w;
;                 }
;                 ss += __shfl_xor(ss, 16); ss += __shfl_xor(ss, 32);
;                 if (fq == 0) __hip_atomic_fetch_add(sumsq_next + row, ss, __ATOMIC_RELAXED, __HIP_MEMORY_SCOPE_AGENT);
;                 asm volatile("" ::: "memory");
.LBB0_1429:
	s_or_b64 exec, exec, s[28:29]
	v_or_b32_e32 v98, 32, v148
	s_waitcnt lgkmcnt(0)
	v_ashrrev_i32_e32 v99, 31, v98
	v_lshlrev_b64 v[100:101], 10, v[98:99]
	v_lshl_add_u64 v[108:109], v[100:101], 0, v[146:147]
	v_lshlrev_b64 v[110:111], 2, v[108:109]
	v_lshl_add_u64 v[112:113], s[8:9], 0, v[110:111]
	global_load_dwordx4 v[100:103], v[112:113], off
	global_load_dwordx4 v[104:107], v[112:113], off offset:16
	v_lshlrev_b64 v[108:109], 1, v[108:109]
	v_lshl_add_u64 v[110:111], s[10:11], 0, v[110:111]
	v_lshl_add_u64 v[114:115], s[64:65], 0, v[108:109]
	v_or_b32_e32 v108, 0x100, v108
	s_waitcnt vmcnt(1)
	v_pk_add_f32 v[96:97], v[96:97], v[102:103]
	v_pk_add_f32 v[94:95], v[94:95], v[100:101]
	s_waitcnt vmcnt(0)
	v_pk_add_f32 v[92:93], v[92:93], v[106:107]
	v_pk_add_f32 v[90:91], v[90:91], v[104:105]
	v_cvt_pk_bf16_f32 v100, v94, v95
	v_cvt_pk_bf16_f32 v101, v96, v97
	v_cvt_pk_bf16_f32 v102, v90, v91
	v_cvt_pk_bf16_f32 v103, v92, v93
	global_store_dwordx4 v[110:111], v[94:97], off
	global_store_dwordx4 v[110:111], v[90:93], off offset:16
	global_store_dwordx4 v[114:115], v[100:103], off
	global_load_dwordx4 v[100:103], v[112:113], off offset:512
	s_nop 0
	global_load_dwordx4 v[104:107], v[112:113], off offset:528
	v_pk_mul_f32 v[90:91], v[90:91], v[90:91]
	v_pk_mul_f32 v[92:93], v[92:93], v[92:93]
	v_pk_fma_f32 v[90:91], v[94:95], v[94:95], v[90:91]
	v_pk_fma_f32 v[92:93], v[96:97], v[96:97], v[92:93]
	v_add_f32_e32 v90, v90, v91
	v_add_f32_e32 v90, v92, v90
	v_add_f32_e32 v94, v93, v90
	s_waitcnt vmcnt(1)
	v_pk_add_f32 v[86:87], v[86:87], v[100:101]
	s_waitcnt vmcnt(0)
	v_pk_add_f32 v[90:91], v[82:83], v[104:105]
	v_pk_add_f32 v[92:93], v[84:85], v[106:107]
	v_pk_mul_f32 v[84:85], v[90:91], v[90:91]
	v_pk_add_f32 v[88:89], v[88:89], v[102:103]
	v_pk_fma_f32 v[84:85], v[86:87], v[86:87], v[84:85]
	v_pk_mul_f32 v[82:83], v[92:93], v[92:93]
	v_add_f32_e32 v84, v94, v84
	v_pk_fma_f32 v[82:83], v[88:89], v[88:89], v[82:83]
	v_add_f32_e32 v84, v85, v84
	v_add_f32_e32 v82, v82, v84
	v_add_f32_e32 v82, v83, v82
	v_mov_b32_e32 v83, v82
	s_nop 1
	v_permlane16_swap_b32_e32 v82, v83
	global_store_dwordx4 v[110:111], v[86:89], off offset:512
	v_lshl_add_u64 v[94:95], s[64:65], 0, v[108:109]
	v_cvt_pk_bf16_f32 v84, v86, v87
	v_cvt_pk_bf16_f32 v85, v88, v89
	s_waitcnt lgkmcnt(0)
	v_add_f32_e32 v82, v82, v83
	v_mov_b32_e32 v83, v82
	s_nop 1
	v_permlane32_swap_b32_e32 v82, v83
	v_cvt_pk_bf16_f32 v86, v90, v91
	v_cvt_pk_bf16_f32 v87, v92, v93
	global_store_dwordx4 v[110:111], v[90:93], off offset:528
	global_store_dwordx4 v[94:95], v[84:87], off
	s_and_saveexec_b64 s[28:29], s[2:3]
	s_cbranch_execz .LBB0_1431
	v_lshl_add_u64 v[84:85], v[98:99], 2, s[14:15]
	s_waitcnt lgkmcnt(0)
	v_add_f32_e32 v82, v82, v83
	global_atomic_add_f32 v[84:85], v82, off
.LBB0_1431:
	s_or_b64 exec, exec, s[28:29]
	v_or_b32_e32 v82, 48, v148
	s_waitcnt lgkmcnt(0)
	v_ashrrev_i32_e32 v83, 31, v82
	v_lshlrev_b64 v[84:85], 10, v[82:83]
	v_lshl_add_u64 v[92:93], v[84:85], 0, v[146:147]
	v_lshlrev_b64 v[94:95], 2, v[92:93]
	v_lshl_add_u64 v[96:97], s[8:9], 0, v[94:95]
	global_load_dwordx4 v[84:87], v[96:97], off
	global_load_dwordx4 v[88:91], v[96:97], off offset:16
	v_lshlrev_b64 v[92:93], 1, v[92:93]
	v_lshl_add_u64 v[94:95], s[10:11], 0, v[94:95]
	v_lshl_add_u64 v[98:99], s[64:65], 0, v[92:93]
	v_or_b32_e32 v92, 0x100, v92
	s_waitcnt vmcnt(1)
	v_pk_add_f32 v[80:81], v[80:81], v[86:87]
	v_pk_add_f32 v[78:79], v[78:79], v[84:85]
	s_waitcnt vmcnt(0)
	v_pk_add_f32 v[76:77], v[76:77], v[90:91]
	v_pk_add_f32 v[74:75], v[74:75], v[88:89]
	v_cvt_pk_bf16_f32 v84, v78, v79
	v_cvt_pk_bf16_f32 v85, v80, v81
	v_cvt_pk_bf16_f32 v86, v74, v75
	v_cvt_pk_bf16_f32 v87, v76, v77
	global_store_dwordx4 v[94:95], v[78:81], off
	global_store_dwordx4 v[94:95], v[74:77], off offset:16
	global_store_dwordx4 v[98:99], v[84:87], off
	global_load_dwordx4 v[84:87], v[96:97], off offset:512
	s_nop 0
	global_load_dwordx4 v[88:91], v[96:97], off offset:528
	v_pk_mul_f32 v[74:75], v[74:75], v[74:75]
	v_pk_mul_f32 v[76:77], v[76:77], v[76:77]
	v_pk_fma_f32 v[74:75], v[78:79], v[78:79], v[74:75]
	v_pk_fma_f32 v[76:77], v[80:81], v[80:81], v[76:77]
	v_add_f32_e32 v74, v74, v75
	v_add_f32_e32 v74, v76, v74
	v_add_f32_e32 v78, v77, v74
	s_waitcnt vmcnt(1)
	v_pk_add_f32 v[70:71], v[70:71], v[84:85]
	s_waitcnt vmcnt(0)
	v_pk_add_f32 v[74:75], v[66:67], v[88:89]
	v_pk_add_f32 v[76:77], v[68:69], v[90:91]
	v_pk_mul_f32 v[68:69], v[74:75], v[74:75]
	v_pk_add_f32 v[72:73], v[72:73], v[86:87]
	v_pk_fma_f32 v[68:69], v[70:71], v[70:71], v[68:69]
	v_pk_mul_f32 v[66:67], v[76:77], v[76:77]
	v_add_f32_e32 v68, v78, v68
	v_pk_fma_f32 v[66:67], v[72:73], v[72:73], v[66:67]
	v_add_f32_e32 v68, v69, v68
	v_add_f32_e32 v66, v66, v68
	v_add_f32_e32 v66, v67, v66
	v_mov_b32_e32 v67, v66
	s_nop 1
	v_permlane16_swap_b32_e32 v66, v67
	global_store_dwordx4 v[94:95], v[70:73], off offset:512
	v_lshl_add_u64 v[78:79], s[64:65], 0, v[92:93]
	v_cvt_pk_bf16_f32 v68, v70, v71
	v_cvt_pk_bf16_f32 v69, v72, v73
	s_waitcnt lgkmcnt(0)
	v_add_f32_e32 v66, v66, v67
	v_mov_b32_e32 v67, v66
	s_nop 1
	v_permlane32_swap_b32_e32 v66, v67
	v_cvt_pk_bf16_f32 v70, v74, v75
	v_cvt_pk_bf16_f32 v71, v76, v77
	global_store_dwordx4 v[94:95], v[74:77], off offset:528
	global_store_dwordx4 v[78:79], v[68:71], off
	s_and_saveexec_b64 s[28:29], s[2:3]
	s_cbranch_execz .LBB0_1433
	v_lshl_add_u64 v[68:69], v[82:83], 2, s[14:15]
	s_waitcnt lgkmcnt(0)
	v_add_f32_e32 v66, v66, v67
	global_atomic_add_f32 v[68:69], v66, off
; DI unsigned pk_bf16(float a, float b) { f32x2 v = {a, b}; bf2_t r = __builtin_convertvector(v, bf2_t); return __builtin_bit_cast(unsigned, r); }
;     DI void operator()(const pg8::f32x4 (&acc)[2][2][4][2], const pg8::Unit& u, int wr, int wc, int fr, int fq) const {
;     ...
;                 const int row = row0 + ai * 128 + m * 16; float ss = 0.f;
;                 const float r2 = sumsq_in ? 1.0f / (sumsq_in[row] * (1.0f / 1024.0f) + EPS) : 1.0f;
; #pragma unroll
;                 for (int bj = 0; bj < 2; ++bj) {
;                     const size_t off = (size_t)row * 1024 + col0 + bj * 128;
;                     f32x4 r0 = *(const f32x4*)(resid + off), r1 = *(const f32x4*)(resid + off + 4);
; #pragma unroll
;                     for (int e = 0; e < 4; ++e) { r0[e] += acc[ai][bj][m][0][e] * r2; r1[e] += acc[ai][bj][m][1][e] * r2; ss += r0[e] * r0[e] + r1[e] * r1[e]; }
;                     *(f32x4*)(hout + off) = r0; *(f32x4*)(hout + off + 4) = r1;
;                     u32x4 w; w.x = pk_bf16(r0[0], r0[1]); w.y = pk_bf16(r0[2], r0[3]); w.z = pk_bf16(r1[0], r1[1]); w.w = pk_bf16(r1[2], r1[3]);
;                     if (hb) *(u32x4*)(hb + off) = w;
;                 }
;                 ss += __shfl_xor(ss, 16); ss += __shfl_xor(ss, 32);
;                 if (fq == 0) __hip_atomic_fetch_add(sumsq_next + row, ss, __ATOMIC_RELAXED, __HIP_MEMORY_SCOPE_AGENT);
;                 asm volatile("" ::: "memory");
.LBB0_1433:
	s_or_b64 exec, exec, s[28:29]
	v_add_u32_e32 v66, 0x80, v148
	s_waitcnt lgkmcnt(0)
	v_ashrrev_i32_e32 v67, 31, v66
	v_lshlrev_b64 v[68:69], 10, v[66:67]
	v_lshl_add_u64 v[76:77], v[68:69], 0, v[146:147]
	v_lshlrev_b64 v[78:79], 2, v[76:77]
	v_lshl_add_u64 v[80:81], s[8:9], 0, v[78:79]
	global_load_dwordx4 v[68:71], v[80:81], off
	global_load_dwordx4 v[72:75], v[80:81], off offset:16
	v_lshlrev_b64 v[76:77], 1, v[76:77]
	v_lshl_add_u64 v[78:79], s[10:11], 0, v[78:79]
	v_lshl_add_u64 v[82:83], s[64:65], 0, v[76:77]
	v_or_b32_e32 v76, 0x100, v76
	s_waitcnt vmcnt(1)
	v_pk_add_f32 v[64:65], v[64:65], v[70:71]
	v_pk_add_f32 v[62:63], v[62:63], v[68:69]
	s_waitcnt vmcnt(0)
	v_pk_add_f32 v[60:61], v[60:61], v[74:75]
	v_pk_add_f32 v[58:59], v[58:59], v[72:73]
	v_cvt_pk_bf16_f32 v68, v62, v63
	v_cvt_pk_bf16_f32 v69, v64, v65
	v_cvt_pk_bf16_f32 v70, v58, v59
	v_cvt_pk_bf16_f32 v71, v60, v61
	global_store_dwordx4 v[78:79], v[62:65], off
	global_store_dwordx4 v[78:79], v[58:61], off offset:16
	global_store_dwordx4 v[82:83], v[68:71], off
	global_load_dwordx4 v[68:71], v[80:81], off offset:512
	s_nop 0
	global_load_dwordx4 v[72:75], v[80:81], off offset:528
	v_pk_mul_f32 v[58:59], v[58:59], v[58:59]
	v_pk_mul_f32 v[60:61], v[60:61], v[60:61]
	v_pk_fma_f32 v[58:59], v[62:63], v[62:63], v[58:59]
	v_pk_fma_f32 v[60:61], v[64:65], v[64:65], v[60:61]
	v_add_f32_e32 v58, v58, v59
	v_add_f32_e32 v58, v60, v58
	v_add_f32_e32 v62, v61, v58
	s_waitcnt vmcnt(1)
	v_pk_add_f32 v[54:55], v[54:55], v[68:69]
	s_waitcnt vmcnt(0)
	v_pk_add_f32 v[58:59], v[50:51], v[72:73]
	v_pk_add_f32 v[60:61], v[52:53], v[74:75]
	v_pk_mul_f32 v[52:53], v[58:59], v[58:59]
	v_pk_add_f32 v[56:57], v[56:57], v[70:71]
	v_pk_fma_f32 v[52:53], v[54:55], v[54:55], v[52:53]
	v_pk_mul_f32 v[50:51], v[60:61], v[60:61]
	v_add_f32_e32 v52, v62, v52
	v_pk_fma_f32 v[50:51], v[56:57], v[56:57], v[50:51]
	v_add_f32_e32 v52, v53, v52
	v_add_f32_e32 v50, v50, v52
	v_add_f32_e32 v50, v51, v50
	v_mov_b32_e32 v51, v50
	s_nop 1
	v_permlane16_swap_b32_e32 v50, v51
	global_store_dwordx4 v[78:79], v[54:57], off offset:512
	v_lshl_add_u64 v[62:63], s[64:65], 0, v[76:77]
	v_cvt_pk_bf16_f32 v52, v54, v55
	v_cvt_pk_bf16_f32 v53, v56, v57
	s_waitcnt lgkmcnt(0)
	v_add_f32_e32 v50, v50, v51
	v_mov_b32_e32 v51, v50
	s_nop 1
	v_permlane32_swap_b32_e32 v50, v51
	v_cvt_pk_bf16_f32 v54, v58, v59
	v_cvt_pk_bf16_f32 v55, v60, v61
	global_store_dwordx4 v[78:79], v[58:61], off offset:528
	global_store_dwordx4 v[62:63], v[52:55], off
	s_and_saveexec_b64 s[28:29], s[2:3]
	s_cbranch_execz .LBB0_1435
	v_lshl_add_u64 v[52:53], v[66:67], 2, s[14:15]
	s_waitcnt lgkmcnt(0)
	v_add_f32_e32 v50, v50, v51
	global_atomic_add_f32 v[52:53], v50, off
.LBB0_1435:
	s_or_b64 exec, exec, s[28:29]
	v_add_u32_e32 v50, 0x90, v148
	s_waitcnt lgkmcnt(0)
	v_ashrrev_i32_e32 v51, 31, v50
	v_lshlrev_b64 v[52:53], 10, v[50:51]
	v_lshl_add_u64 v[60:61], v[52:53], 0, v[146:147]
	v_lshlrev_b64 v[62:63], 2, v[60:61]
	v_lshl_add_u64 v[64:65], s[8:9], 0, v[62:63]
	global_load_dwordx4 v[52:55], v[64:65], off
	global_load_dwordx4 v[56:59], v[64:65], off offset:16
	v_lshlrev_b64 v[60:61], 1, v[60:61]
	v_lshl_add_u64 v[62:63], s[10:11], 0, v[62:63]
	v_lshl_add_u64 v[66:67], s[64:65], 0, v[60:61]
	v_or_b32_e32 v60, 0x100, v60
	s_waitcnt vmcnt(1)
	v_pk_add_f32 v[48:49], v[48:49], v[54:55]
	v_pk_add_f32 v[46:47], v[46:47], v[52:53]
	s_waitcnt vmcnt(0)
	v_pk_add_f32 v[44:45], v[44:45], v[58:59]
	v_pk_add_f32 v[42:43], v[42:43], v[56:57]
	v_cvt_pk_bf16_f32 v52, v46, v47
	v_cvt_pk_bf16_f32 v53, v48, v49
	v_cvt_pk_bf16_f32 v54, v42, v43
	v_cvt_pk_bf16_f32 v55, v44, v45
	global_store_dwordx4 v[62:63], v[46:49], off
	global_store_dwordx4 v[62:63], v[42:45], off offset:16
	global_store_dwordx4 v[66:67], v[52:55], off
	global_load_dwordx4 v[52:55], v[64:65], off offset:512
	s_nop 0
	global_load_dwordx4 v[56:59], v[64:65], off offset:528
	v_pk_mul_f32 v[42:43], v[42:43], v[42:43]
	v_pk_mul_f32 v[44:45], v[44:45], v[44:45]
	v_pk_fma_f32 v[42:43], v[46:47], v[46:47], v[42:43]
	v_pk_fma_f32 v[44:45], v[48:49], v[48:49], v[44:45]
	v_add_f32_e32 v42, v42, v43
	v_add_f32_e32 v42, v44, v42
	v_add_f32_e32 v46, v45, v42
	s_waitcnt vmcnt(1)
	v_pk_add_f32 v[38:39], v[38:39], v[52:53]
	s_waitcnt vmcnt(0)
	v_pk_add_f32 v[42:43], v[34:35], v[56:57]
	v_pk_add_f32 v[44:45], v[36:37], v[58:59]
	v_pk_mul_f32 v[36:37], v[42:43], v[42:43]
	v_pk_add_f32 v[40:41], v[40:41], v[54:55]
	v_pk_fma_f32 v[36:37], v[38:39], v[38:39], v[36:37]
	v_pk_mul_f32 v[34:35], v[44:45], v[44:45]
	v_add_f32_e32 v36, v46, v36
	v_pk_fma_f32 v[34:35], v[40:41], v[40:41], v[34:35]
	v_add_f32_e32 v36, v37, v36
	v_add_f32_e32 v34, v34, v36
	v_add_f32_e32 v34, v35, v34
	v_mov_b32_e32 v35, v34
	s_nop 1
	v_permlane16_swap_b32_e32 v34, v35
	global_store_dwordx4 v[62:63], v[38:41], off offset:512
	v_lshl_add_u64 v[46:47], s[64:65], 0, v[60:61]
	v_cvt_pk_bf16_f32 v36, v38, v39
	v_cvt_pk_bf16_f32 v37, v40, v41
	s_waitcnt lgkmcnt(0)
	v_add_f32_e32 v34, v34, v35
	v_mov_b32_e32 v35, v34
	s_nop 1
	v_permlane32_swap_b32_e32 v34, v35
	v_cvt_pk_bf16_f32 v38, v42, v43
	v_cvt_pk_bf16_f32 v39, v44, v45
	global_store_dwordx4 v[62:63], v[42:45], off offset:528
	global_store_dwordx4 v[46:47], v[36:39], off
	s_and_saveexec_b64 s[28:29], s[2:3]
	s_cbranch_execz .LBB0_1437
	v_lshl_add_u64 v[36:37], v[50:51], 2, s[14:15]
	s_waitcnt lgkmcnt(0)
	v_add_f32_e32 v34, v34, v35
	global_atomic_add_f32 v[36:37], v34, off
; DI unsigned pk_bf16(float a, float b) { f32x2 v = {a, b}; bf2_t r = __builtin_convertvector(v, bf2_t); return __builtin_bit_cast(unsigned, r); }
;     DI void operator()(const pg8::f32x4 (&acc)[2][2][4][2], const pg8::Unit& u, int wr, int wc, int fr, int fq) const {
;     ...
;                 const int row = row0 + ai * 128 + m * 16; float ss = 0.f;
;                 const float r2 = sumsq_in ? 1.0f / (sumsq_in[row] * (1.0f / 1024.0f) + EPS) : 1.0f;
; #pragma unroll
;                 for (int bj = 0; bj < 2; ++bj) {
;                     const size_t off = (size_t)row * 1024 + col0 + bj * 128;
;                     f32x4 r0 = *(const f32x4*)(resid + off), r1 = *(const f32x4*)(resid + off + 4);
; #pragma unroll
;                     for (int e = 0; e < 4; ++e) { r0[e] += acc[ai][bj][m][0][e] * r2; r1[e] += acc[ai][bj][m][1][e] * r2; ss += r0[e] * r0[e] + r1[e] * r1[e]; }
;                     *(f32x4*)(hout + off) = r0; *(f32x4*)(hout + off + 4) = r1;
;                     u32x4 w; w.x = pk_bf16(r0[0], r0[1]); w.y = pk_bf16(r0[2], r0[3]); w.z = pk_bf16(r1[0], r1[1]); w.w = pk_bf16(r1[2], r1[3]);
;                     if (hb) *(u32x4*)(hb + off) = w;
;                 }
;                 ss += __shfl_xor(ss, 16); ss += __shfl_xor(ss, 32);
;                 if (fq == 0) __hip_atomic_fetch_add(sumsq_next + row, ss, __ATOMIC_RELAXED, __HIP_MEMORY_SCOPE_AGENT);
;                 asm volatile("" ::: "memory");
.LBB0_1437:
	s_or_b64 exec, exec, s[28:29]
	v_add_u32_e32 v34, 0xa0, v148
	s_waitcnt lgkmcnt(0)
	v_ashrrev_i32_e32 v35, 31, v34
	v_lshlrev_b64 v[36:37], 10, v[34:35]
	v_lshl_add_u64 v[44:45], v[36:37], 0, v[146:147]
	v_lshlrev_b64 v[46:47], 2, v[44:45]
	v_lshl_add_u64 v[48:49], s[8:9], 0, v[46:47]
	global_load_dwordx4 v[36:39], v[48:49], off
	global_load_dwordx4 v[40:43], v[48:49], off offset:16
	v_lshlrev_b64 v[44:45], 1, v[44:45]
	v_lshl_add_u64 v[46:47], s[10:11], 0, v[46:47]
	v_lshl_add_u64 v[50:51], s[64:65], 0, v[44:45]
	v_or_b32_e32 v44, 0x100, v44
	s_waitcnt vmcnt(1)
	v_pk_add_f32 v[32:33], v[32:33], v[38:39]
	v_pk_add_f32 v[30:31], v[30:31], v[36:37]
	s_waitcnt vmcnt(0)
	v_pk_add_f32 v[28:29], v[28:29], v[42:43]
	v_pk_add_f32 v[26:27], v[26:27], v[40:41]
	v_cvt_pk_bf16_f32 v36, v30, v31
	v_cvt_pk_bf16_f32 v37, v32, v33
	v_cvt_pk_bf16_f32 v38, v26, v27
	v_cvt_pk_bf16_f32 v39, v28, v29
	global_store_dwordx4 v[46:47], v[30:33], off
	global_store_dwordx4 v[46:47], v[26:29], off offset:16
	global_store_dwordx4 v[50:51], v[36:39], off
	global_load_dwordx4 v[36:39], v[48:49], off offset:512
	s_nop 0
	global_load_dwordx4 v[40:43], v[48:49], off offset:528
	v_pk_mul_f32 v[26:27], v[26:27], v[26:27]
	v_pk_mul_f32 v[28:29], v[28:29], v[28:29]
	v_pk_fma_f32 v[26:27], v[30:31], v[30:31], v[26:27]
	v_pk_fma_f32 v[28:29], v[32:33], v[32:33], v[28:29]
	v_add_f32_e32 v26, v26, v27
	v_add_f32_e32 v26, v28, v26
	v_add_f32_e32 v30, v29, v26
	s_waitcnt vmcnt(1)
	v_pk_add_f32 v[22:23], v[22:23], v[36:37]
	s_waitcnt vmcnt(0)
	v_pk_add_f32 v[26:27], v[18:19], v[40:41]
	v_pk_add_f32 v[28:29], v[20:21], v[42:43]
	v_pk_mul_f32 v[20:21], v[26:27], v[26:27]
	v_pk_add_f32 v[24:25], v[24:25], v[38:39]
	v_pk_fma_f32 v[20:21], v[22:23], v[22:23], v[20:21]
	v_pk_mul_f32 v[18:19], v[28:29], v[28:29]
	v_add_f32_e32 v20, v30, v20
	v_pk_fma_f32 v[18:19], v[24:25], v[24:25], v[18:19]
	v_add_f32_e32 v20, v21, v20
	v_add_f32_e32 v18, v18, v20
	v_add_f32_e32 v18, v19, v18
	v_mov_b32_e32 v19, v18
	s_nop 1
	v_permlane16_swap_b32_e32 v18, v19
	global_store_dwordx4 v[46:47], v[22:25], off offset:512
	v_lshl_add_u64 v[30:31], s[64:65], 0, v[44:45]
	v_cvt_pk_bf16_f32 v20, v22, v23
	v_cvt_pk_bf16_f32 v21, v24, v25
	s_waitcnt lgkmcnt(0)
	v_add_f32_e32 v18, v18, v19
	v_mov_b32_e32 v19, v18
	s_nop 1
	v_permlane32_swap_b32_e32 v18, v19
	v_cvt_pk_bf16_f32 v22, v26, v27
	v_cvt_pk_bf16_f32 v23, v28, v29
	global_store_dwordx4 v[46:47], v[26:29], off offset:528
	global_store_dwordx4 v[30:31], v[20:23], off
	s_and_saveexec_b64 s[28:29], s[2:3]
	s_cbranch_execz .LBB0_1439
	v_lshl_add_u64 v[20:21], v[34:35], 2, s[14:15]
	s_waitcnt lgkmcnt(0)
	v_add_f32_e32 v18, v18, v19
	global_atomic_add_f32 v[20:21], v18, off
.LBB0_1439:
	s_or_b64 exec, exec, s[28:29]
	v_add_u32_e32 v18, 0xb0, v148
	s_waitcnt lgkmcnt(0)
	v_ashrrev_i32_e32 v19, 31, v18
	v_lshlrev_b64 v[20:21], 10, v[18:19]
	v_lshl_add_u64 v[28:29], v[20:21], 0, v[146:147]
	v_lshlrev_b64 v[30:31], 2, v[28:29]
	v_lshl_add_u64 v[32:33], s[8:9], 0, v[30:31]
	global_load_dwordx4 v[20:23], v[32:33], off
	global_load_dwordx4 v[24:27], v[32:33], off offset:16
	v_lshlrev_b64 v[28:29], 1, v[28:29]
	v_lshl_add_u64 v[30:31], s[10:11], 0, v[30:31]
	v_lshl_add_u64 v[34:35], s[64:65], 0, v[28:29]
	v_or_b32_e32 v28, 0x100, v28
	s_waitcnt vmcnt(1)
	v_pk_add_f32 v[16:17], v[16:17], v[22:23]
	v_pk_add_f32 v[14:15], v[14:15], v[20:21]
	s_waitcnt vmcnt(0)
	v_pk_add_f32 v[12:13], v[12:13], v[26:27]
	v_pk_add_f32 v[10:11], v[10:11], v[24:25]
	v_cvt_pk_bf16_f32 v20, v14, v15
	v_cvt_pk_bf16_f32 v21, v16, v17
	v_cvt_pk_bf16_f32 v22, v10, v11
	v_cvt_pk_bf16_f32 v23, v12, v13
	global_store_dwordx4 v[30:31], v[14:17], off
	global_store_dwordx4 v[30:31], v[10:13], off offset:16
	global_store_dwordx4 v[34:35], v[20:23], off
	global_load_dwordx4 v[20:23], v[32:33], off offset:512
	s_nop 0
	global_load_dwordx4 v[24:27], v[32:33], off offset:528
	v_pk_mul_f32 v[10:11], v[10:11], v[10:11]
	v_pk_mul_f32 v[12:13], v[12:13], v[12:13]
	v_pk_fma_f32 v[10:11], v[14:15], v[14:15], v[10:11]
	v_pk_fma_f32 v[12:13], v[16:17], v[16:17], v[12:13]
	v_add_f32_e32 v10, v10, v11
	v_add_f32_e32 v10, v12, v10
	v_add_f32_e32 v14, v13, v10
	s_waitcnt vmcnt(1)
	v_pk_add_f32 v[6:7], v[6:7], v[20:21]
	s_waitcnt vmcnt(0)
	v_pk_add_f32 v[10:11], v[2:3], v[24:25]
	v_pk_add_f32 v[12:13], v[4:5], v[26:27]
	v_pk_mul_f32 v[4:5], v[10:11], v[10:11]
	v_pk_add_f32 v[8:9], v[8:9], v[22:23]
	v_pk_fma_f32 v[4:5], v[6:7], v[6:7], v[4:5]
	v_pk_mul_f32 v[2:3], v[12:13], v[12:13]
	v_add_f32_e32 v4, v14, v4
	v_pk_fma_f32 v[2:3], v[8:9], v[8:9], v[2:3]
	v_add_f32_e32 v4, v5, v4
	v_add_f32_e32 v2, v2, v4
	v_add_f32_e32 v2, v3, v2
	v_mov_b32_e32 v3, v2
	s_nop 1
	v_permlane16_swap_b32_e32 v2, v3
	global_store_dwordx4 v[30:31], v[6:9], off offset:512
	v_lshl_add_u64 v[14:15], s[64:65], 0, v[28:29]
	v_cvt_pk_bf16_f32 v4, v6, v7
	v_cvt_pk_bf16_f32 v5, v8, v9
	s_waitcnt lgkmcnt(0)
	v_add_f32_e32 v2, v2, v3
	v_mov_b32_e32 v3, v2
	s_nop 1
	v_permlane32_swap_b32_e32 v2, v3
	v_cvt_pk_bf16_f32 v6, v10, v11
	v_cvt_pk_bf16_f32 v7, v12, v13
	global_store_dwordx4 v[30:31], v[10:13], off offset:528
	global_store_dwordx4 v[14:15], v[4:7], off
	s_and_saveexec_b64 s[28:29], s[2:3]
	s_cbranch_execz .LBB0_1441
	v_lshl_add_u64 v[4:5], v[18:19], 2, s[14:15]
	s_waitcnt lgkmcnt(0)
	v_add_f32_e32 v2, v2, v3
	global_atomic_add_f32 v[4:5], v2, off

; DI unsigned pk_bf16(float a, float b) { f32x2 v = {a, b}; bf2_t r = __builtin_convertvector(v, bf2_t); return __builtin_bit_cast(unsigned, r); }
;     DI void operator()(const pg8::f32x4 (&acc)[2][2][4][2], const pg8::Unit& u, int wr, int wc, int fr, int fq) const {
;     ...
;                 const int row = row0 + ai * 128 + m * 16; float ss = 0.f;
;                 const float r2 = sumsq_in ? 1.0f / (sumsq_in[row] * (1.0f / 1024.0f) + EPS) : 1.0f;
; #pragma unroll
;                 for (int bj = 0; bj < 2; ++bj) {
;                     const size_t off = (size_t)row * 1024 + col0 + bj * 128;
;                     f32x4 r0 = *(const f32x4*)(resid + off), r1 = *(const f32x4*)(resid + off + 4);
; #pragma unroll
;                     for (int e = 0; e < 4; ++e) { r0[e] += acc[ai][bj][m][0][e] * r2; r1[e] += acc[ai][bj][m][1][e] * r2; ss += r0[e] * r0[e] + r1[e] * r1[e]; }
;                     *(f32x4*)(hout + off) = r0; *(f32x4*)(hout + off + 4) = r1;
;                     u32x4 w; w.x = pk_bf16(r0[0], r0[1]); w.y = pk_bf16(r0[2], r0[3]); w.z = pk_bf16(r1[0], r1[1]); w.w = pk_bf16(r1[2], r1[3]);
;                     if (hb) *(u32x4*)(hb + off) = w;
;                 }
;                 ss += __shfl_xor(ss, 16); ss += __shfl_xor(ss, 32);
;                 if (fq == 0) __hip_atomic_fetch_add(sumsq_next + row, ss, __ATOMIC_RELAXED, __HIP_MEMORY_SCOPE_AGENT);
;                 asm volatile("" ::: "memory");
.LBB0_1511:
	v_lshl_add_u32 v146, s30, 8, v1
	v_ashrrev_i32_e32 v147, 31, v146
	v_lshl_add_u64 v[150:151], v[146:147], 2, s[14:15]
	global_load_dword v159, v[150:151], off
	v_lshl_or_b32 v148, s28, 8, v153
	v_ashrrev_i32_e32 v149, 31, v148
	v_lshlrev_b64 v[160:161], 10, v[146:147]
	v_lshl_add_u64 v[168:169], v[160:161], 0, v[148:149]
	v_lshl_add_u64 v[172:173], v[168:169], 2, s[8:9]
	global_load_dwordx4 v[160:163], v[172:173], off
	global_load_dwordx4 v[164:167], v[172:173], off offset:16
	v_lshlrev_b64 v[174:175], 1, v[168:169]
	v_lshl_add_u64 v[168:169], s[64:65], 0, v[174:175]
	v_or_b32_e32 v174, 0x100, v174
	s_waitcnt vmcnt(0)
	v_fmamk_f32 v159, v159, 0x3a800000, v158
	v_div_scale_f32 v170, s[0:1], v159, v159, 1.0
	v_rcp_f32_e32 v171, v170
	v_div_scale_f32 v176, vcc, 1.0, v159, 1.0
	v_fma_f32 v177, -v170, v171, 1.0
	v_fmac_f32_e32 v171, v177, v171
	v_mul_f32_e32 v177, v176, v171
	v_fma_f32 v178, -v170, v177, v176
	v_fmac_f32_e32 v177, v178, v171
	v_fma_f32 v170, -v170, v177, v176
	v_div_fmas_f32 v170, v170, v171, v177
	v_div_fixup_f32 v176, v170, v159, 1.0
	v_pk_fma_f32 v[126:127], v[126:127], v[176:177], v[160:161] op_sel_hi:[1,0,1]
	v_pk_fma_f32 v[160:161], v[122:123], v[176:177], v[164:165] op_sel_hi:[1,0,1]
	v_pk_fma_f32 v[128:129], v[128:129], v[176:177], v[162:163] op_sel_hi:[1,0,1]
	v_pk_fma_f32 v[162:163], v[124:125], v[176:177], v[166:167] op_sel_hi:[1,0,1]
	v_cvt_pk_bf16_f32 v122, v126, v127
	v_cvt_pk_bf16_f32 v123, v128, v129
	v_cvt_pk_bf16_f32 v124, v160, v161
	v_cvt_pk_bf16_f32 v125, v162, v163
	global_store_dwordx4 v[172:173], v[126:129], off
	global_store_dwordx4 v[172:173], v[160:163], off offset:16
	global_store_dwordx4 v[168:169], v[122:125], off
	global_load_dwordx4 v[164:167], v[172:173], off offset:512
	s_nop 0
	global_load_dwordx4 v[168:171], v[172:173], off offset:528
	v_and_b32_e32 v123, 64, v157
	v_xor_b32_e32 v122, 16, v157
	v_add_u32_e32 v123, 64, v123
	v_xor_b32_e32 v124, 32, v157
	v_cmp_lt_i32_e32 vcc, v122, v123
	s_waitcnt vmcnt(1)
	v_pk_fma_f32 v[118:119], v[118:119], v[176:177], v[164:165] op_sel_hi:[1,0,1]
	v_cndmask_b32_e32 v122, v157, v122, vcc
	v_cmp_lt_i32_e32 vcc, v124, v123
	v_lshlrev_b32_e32 v123, 2, v122
	v_pk_fma_f32 v[120:121], v[120:121], v[176:177], v[166:167] op_sel_hi:[1,0,1]
	v_cndmask_b32_e32 v124, v157, v124, vcc
	v_lshlrev_b32_e32 v122, 2, v124
	v_pk_mul_f32 v[124:125], v[160:161], v[160:161]
	v_pk_mul_f32 v[160:161], v[162:163], v[162:163]
	v_pk_fma_f32 v[124:125], v[126:127], v[126:127], v[124:125]
	v_pk_fma_f32 v[126:127], v[128:129], v[128:129], v[160:161]
	v_add_f32_e32 v124, v124, v125
	v_add_f32_e32 v124, v126, v124
	v_add_f32_e32 v128, v127, v124
	s_waitcnt vmcnt(0)
	v_pk_fma_f32 v[124:125], v[114:115], v[176:177], v[168:169] op_sel_hi:[1,0,1]
	v_pk_fma_f32 v[126:127], v[116:117], v[176:177], v[170:171] op_sel_hi:[1,0,1]
	v_pk_mul_f32 v[114:115], v[124:125], v[124:125]
	v_pk_mul_f32 v[116:117], v[126:127], v[126:127]
	v_pk_fma_f32 v[114:115], v[118:119], v[118:119], v[114:115]
	v_pk_fma_f32 v[116:117], v[120:121], v[120:121], v[116:117]
	v_add_f32_e32 v114, v128, v114
	v_add_f32_e32 v114, v115, v114
	v_add_f32_e32 v114, v116, v114
	v_add_f32_e32 v114, v117, v114
	v_mov_b32_e32 v115, v114
	s_nop 1
	v_permlane16_swap_b32_e32 v114, v115
	global_store_dwordx4 v[172:173], v[118:121], off offset:512
	v_lshl_add_u64 v[128:129], s[64:65], 0, v[174:175]
	v_cvt_pk_bf16_f32 v116, v118, v119
	v_cvt_pk_bf16_f32 v117, v120, v121
	s_waitcnt lgkmcnt(0)
	v_add_f32_e32 v114, v114, v115
	v_mov_b32_e32 v115, v114
	s_nop 1
	v_permlane32_swap_b32_e32 v114, v115
	v_cvt_pk_bf16_f32 v118, v124, v125
	v_cvt_pk_bf16_f32 v119, v126, v127
	global_store_dwordx4 v[172:173], v[124:127], off offset:528
	global_store_dwordx4 v[128:129], v[116:119], off
	s_and_saveexec_b64 s[28:29], s[2:3]
	s_cbranch_execz .LBB0_1513
	v_lshl_add_u64 v[116:117], v[146:147], 2, s[12:13]
	s_waitcnt lgkmcnt(0)
	v_add_f32_e32 v114, v114, v115
	global_atomic_add_f32 v[116:117], v114, off
.LBB0_1513:
	s_or_b64 exec, exec, s[28:29]
	v_or_b32_e32 v114, 16, v146
	s_waitcnt lgkmcnt(0)
	v_ashrrev_i32_e32 v115, 31, v114
	v_lshl_add_u64 v[116:117], v[114:115], 2, s[14:15]
	global_load_dword v147, v[116:117], off
	v_lshlrev_b64 v[116:117], 10, v[114:115]
	v_lshl_add_u64 v[120:121], v[116:117], 0, v[148:149]
	v_lshl_add_u64 v[128:129], v[120:121], 2, s[8:9]
	global_load_dwordx4 v[116:119], v[128:129], off
	global_load_dwordx4 v[124:127], v[128:129], off offset:16
	v_lshlrev_b64 v[120:121], 1, v[120:121]
	v_lshl_add_u64 v[160:161], s[64:65], 0, v[120:121]
	v_or_b32_e32 v120, 0x100, v120
	s_waitcnt vmcnt(2)
	v_fmamk_f32 v147, v147, 0x3a800000, v158
	v_div_scale_f32 v159, s[0:1], v147, v147, 1.0
	v_rcp_f32_e32 v162, v159
	v_div_scale_f32 v163, vcc, 1.0, v147, 1.0
	v_fma_f32 v164, -v159, v162, 1.0
	v_fmac_f32_e32 v162, v164, v162
	v_mul_f32_e32 v164, v163, v162
	v_fma_f32 v165, -v159, v164, v163
	v_fmac_f32_e32 v164, v165, v162
	v_fma_f32 v159, -v159, v164, v163
	v_div_fmas_f32 v159, v159, v162, v164
	v_div_fixup_f32 v162, v159, v147, 1.0
	s_waitcnt vmcnt(1)
	v_pk_fma_f32 v[110:111], v[110:111], v[162:163], v[116:117] op_sel_hi:[1,0,1]
	s_waitcnt vmcnt(0)
; DI unsigned pk_bf16(float a, float b) { f32x2 v = {a, b}; bf2_t r = __builtin_convertvector(v, bf2_t); return __builtin_bit_cast(unsigned, r); }
;     DI void operator()(const pg8::f32x4 (&acc)[2][2][4][2], const pg8::Unit& u, int wr, int wc, int fr, int fq) const {
;     ...
;                 const int row = row0 + ai * 128 + m * 16; float ss = 0.f;
;                 const float r2 = sumsq_in ? 1.0f / (sumsq_in[row] * (1.0f / 1024.0f) + EPS) : 1.0f;
; #pragma unroll
;                 for (int bj = 0; bj < 2; ++bj) {
;                     const size_t off = (size_t)row * 1024 + col0 + bj * 128;
;                     f32x4 r0 = *(const f32x4*)(resid + off), r1 = *(const f32x4*)(resid + off + 4);
; #pragma unroll
;                     for (int e = 0; e < 4; ++e) { r0[e] += acc[ai][bj][m][0][e] * r2; r1[e] += acc[ai][bj][m][1][e] * r2; ss += r0[e] * r0[e] + r1[e] * r1[e]; }
;                     *(f32x4*)(hout + off) = r0; *(f32x4*)(hout + off + 4) = r1;
;                     u32x4 w; w.x = pk_bf16(r0[0], r0[1]); w.y = pk_bf16(r0[2], r0[3]); w.z = pk_bf16(r1[0], r1[1]); w.w = pk_bf16(r1[2], r1[3]);
;                     if (hb) *(u32x4*)(hb + off) = w;
;                 }
;                 ss += __shfl_xor(ss, 16); ss += __shfl_xor(ss, 32);
;                 if (fq == 0) __hip_atomic_fetch_add(sumsq_next + row, ss, __ATOMIC_RELAXED, __HIP_MEMORY_SCOPE_AGENT);
;                 asm volatile("" ::: "memory");
	v_pk_fma_f32 v[106:107], v[106:107], v[162:163], v[124:125] op_sel_hi:[1,0,1]
	v_pk_fma_f32 v[112:113], v[112:113], v[162:163], v[118:119] op_sel_hi:[1,0,1]
	v_pk_fma_f32 v[108:109], v[108:109], v[162:163], v[126:127] op_sel_hi:[1,0,1]
	v_cvt_pk_bf16_f32 v116, v110, v111
	v_cvt_pk_bf16_f32 v117, v112, v113
	v_cvt_pk_bf16_f32 v118, v106, v107
	v_cvt_pk_bf16_f32 v119, v108, v109
	global_store_dwordx4 v[128:129], v[110:113], off
	global_store_dwordx4 v[128:129], v[106:109], off offset:16
	global_store_dwordx4 v[160:161], v[116:119], off
	global_load_dwordx4 v[116:119], v[128:129], off offset:512
	s_nop 0
	global_load_dwordx4 v[124:127], v[128:129], off offset:528
	v_pk_mul_f32 v[106:107], v[106:107], v[106:107]
	v_pk_mul_f32 v[108:109], v[108:109], v[108:109]
	v_pk_fma_f32 v[106:107], v[110:111], v[110:111], v[106:107]
	v_pk_fma_f32 v[108:109], v[112:113], v[112:113], v[108:109]
	v_add_f32_e32 v106, v106, v107
	v_add_f32_e32 v106, v108, v106
	v_add_f32_e32 v110, v109, v106
	s_waitcnt vmcnt(1)
	v_pk_fma_f32 v[102:103], v[102:103], v[162:163], v[116:117] op_sel_hi:[1,0,1]
	s_waitcnt vmcnt(0)
	v_pk_fma_f32 v[106:107], v[98:99], v[162:163], v[124:125] op_sel_hi:[1,0,1]
	v_pk_fma_f32 v[108:109], v[100:101], v[162:163], v[126:127] op_sel_hi:[1,0,1]
	v_pk_mul_f32 v[98:99], v[106:107], v[106:107]
	v_pk_fma_f32 v[104:105], v[104:105], v[162:163], v[118:119] op_sel_hi:[1,0,1]
	v_pk_fma_f32 v[98:99], v[102:103], v[102:103], v[98:99]
	v_pk_mul_f32 v[100:101], v[108:109], v[108:109]
	v_add_f32_e32 v98, v110, v98
	v_pk_fma_f32 v[100:101], v[104:105], v[104:105], v[100:101]
	v_add_f32_e32 v98, v99, v98
	v_add_f32_e32 v98, v100, v98
	v_add_f32_e32 v98, v101, v98
	v_mov_b32_e32 v99, v98
	s_nop 1
	v_permlane16_swap_b32_e32 v98, v99
	global_store_dwordx4 v[128:129], v[102:105], off offset:512
	v_lshl_add_u64 v[110:111], s[64:65], 0, v[120:121]
	v_cvt_pk_bf16_f32 v100, v102, v103
	v_cvt_pk_bf16_f32 v101, v104, v105
	s_waitcnt lgkmcnt(0)
	v_add_f32_e32 v98, v98, v99
	v_mov_b32_e32 v99, v98
	s_nop 1
	v_permlane32_swap_b32_e32 v98, v99
	v_cvt_pk_bf16_f32 v102, v106, v107
	v_cvt_pk_bf16_f32 v103, v108, v109
	global_store_dwordx4 v[128:129], v[106:109], off offset:528
	global_store_dwordx4 v[110:111], v[100:103], off
	s_and_saveexec_b64 s[28:29], s[2:3]
	s_cbranch_execz .LBB0_1515
	v_lshl_add_u64 v[100:101], v[114:115], 2, s[12:13]
	s_waitcnt lgkmcnt(0)
	v_add_f32_e32 v98, v98, v99
	global_atomic_add_f32 v[100:101], v98, off
.LBB0_1515:
	s_or_b64 exec, exec, s[28:29]
	v_or_b32_e32 v98, 32, v146
	s_waitcnt lgkmcnt(0)
	v_ashrrev_i32_e32 v99, 31, v98
	v_lshl_add_u64 v[100:101], v[98:99], 2, s[14:15]
	global_load_dword v112, v[100:101], off
	v_lshlrev_b64 v[100:101], 10, v[98:99]
	v_lshl_add_u64 v[108:109], v[100:101], 0, v[148:149]
	v_lshl_add_u64 v[110:111], v[108:109], 2, s[8:9]
	global_load_dwordx4 v[100:103], v[110:111], off
	global_load_dwordx4 v[104:107], v[110:111], off offset:16
	v_lshlrev_b64 v[108:109], 1, v[108:109]
	s_waitcnt vmcnt(2)
	v_fmamk_f32 v114, v112, 0x3a800000, v158
	v_div_scale_f32 v115, s[0:1], v114, v114, 1.0
	v_rcp_f32_e32 v116, v115
	v_div_scale_f32 v117, vcc, 1.0, v114, 1.0
	v_lshl_add_u64 v[112:113], s[64:65], 0, v[108:109]
	v_fma_f32 v118, -v115, v116, 1.0
	v_fmac_f32_e32 v116, v118, v116
	v_mul_f32_e32 v118, v117, v116
	v_fma_f32 v119, -v115, v118, v117
	v_fmac_f32_e32 v118, v119, v116
	v_fma_f32 v115, -v115, v118, v117
	v_div_fmas_f32 v115, v115, v116, v118
	v_div_fixup_f32 v114, v115, v114, 1.0
	s_waitcnt vmcnt(1)
	v_pk_fma_f32 v[94:95], v[94:95], v[114:115], v[100:101] op_sel_hi:[1,0,1]
	s_waitcnt vmcnt(0)
	v_pk_fma_f32 v[90:91], v[90:91], v[114:115], v[104:105] op_sel_hi:[1,0,1]
	v_pk_fma_f32 v[96:97], v[96:97], v[114:115], v[102:103] op_sel_hi:[1,0,1]
	v_pk_fma_f32 v[92:93], v[92:93], v[114:115], v[106:107] op_sel_hi:[1,0,1]
	v_cvt_pk_bf16_f32 v100, v94, v95
	v_cvt_pk_bf16_f32 v101, v96, v97
	v_cvt_pk_bf16_f32 v102, v90, v91
	v_cvt_pk_bf16_f32 v103, v92, v93
	global_store_dwordx4 v[110:111], v[94:97], off
	global_store_dwordx4 v[110:111], v[90:93], off offset:16
	global_store_dwordx4 v[112:113], v[100:103], off
	global_load_dwordx4 v[100:103], v[110:111], off offset:512
	s_nop 0
	global_load_dwordx4 v[104:107], v[110:111], off offset:528
	v_pk_mul_f32 v[90:91], v[90:91], v[90:91]
	v_pk_mul_f32 v[92:93], v[92:93], v[92:93]
	v_pk_fma_f32 v[90:91], v[94:95], v[94:95], v[90:91]
	v_pk_fma_f32 v[92:93], v[96:97], v[96:97], v[92:93]
	v_add_f32_e32 v90, v90, v91
	v_add_f32_e32 v90, v92, v90
	v_add_f32_e32 v94, v93, v90
	v_or_b32_e32 v108, 0x100, v108
	s_waitcnt vmcnt(1)
	v_pk_fma_f32 v[86:87], v[86:87], v[114:115], v[100:101] op_sel_hi:[1,0,1]
	s_waitcnt vmcnt(0)
	v_pk_fma_f32 v[90:91], v[82:83], v[114:115], v[104:105] op_sel_hi:[1,0,1]
	v_pk_fma_f32 v[92:93], v[84:85], v[114:115], v[106:107] op_sel_hi:[1,0,1]
	v_pk_mul_f32 v[82:83], v[90:91], v[90:91]
	v_pk_fma_f32 v[88:89], v[88:89], v[114:115], v[102:103] op_sel_hi:[1,0,1]
	v_pk_fma_f32 v[82:83], v[86:87], v[86:87], v[82:83]
	v_pk_mul_f32 v[84:85], v[92:93], v[92:93]
	v_add_f32_e32 v82, v94, v82
	v_pk_fma_f32 v[84:85], v[88:89], v[88:89], v[84:85]
	v_add_f32_e32 v82, v83, v82
	v_add_f32_e32 v82, v84, v82
	v_add_f32_e32 v82, v85, v82
	v_mov_b32_e32 v83, v82
	s_nop 1
	v_permlane16_swap_b32_e32 v82, v83
	global_store_dwordx4 v[110:111], v[86:89], off offset:512
	v_lshl_add_u64 v[94:95], s[64:65], 0, v[108:109]
	v_cvt_pk_bf16_f32 v84, v86, v87
	v_cvt_pk_bf16_f32 v85, v88, v89
	s_waitcnt lgkmcnt(0)
	v_add_f32_e32 v82, v82, v83
	v_mov_b32_e32 v83, v82
	s_nop 1
	v_permlane32_swap_b32_e32 v82, v83
	v_cvt_pk_bf16_f32 v86, v90, v91
	v_cvt_pk_bf16_f32 v87, v92, v93
	global_store_dwordx4 v[110:111], v[90:93], off offset:528
	global_store_dwordx4 v[94:95], v[84:87], off
	s_and_saveexec_b64 s[28:29], s[2:3]
	s_cbranch_execz .LBB0_1517
	v_lshl_add_u64 v[84:85], v[98:99], 2, s[12:13]
	s_waitcnt lgkmcnt(0)
	v_add_f32_e32 v82, v82, v83
	global_atomic_add_f32 v[84:85], v82, off
; DI unsigned pk_bf16(float a, float b) { f32x2 v = {a, b}; bf2_t r = __builtin_convertvector(v, bf2_t); return __builtin_bit_cast(unsigned, r); }
;     DI void operator()(const pg8::f32x4 (&acc)[2][2][4][2], const pg8::Unit& u, int wr, int wc, int fr, int fq) const {
;     ...
;                 const int row = row0 + ai * 128 + m * 16; float ss = 0.f;
;                 const float r2 = sumsq_in ? 1.0f / (sumsq_in[row] * (1.0f / 1024.0f) + EPS) : 1.0f;
; #pragma unroll
;                 for (int bj = 0; bj < 2; ++bj) {
;                     const size_t off = (size_t)row * 1024 + col0 + bj * 128;
;                     f32x4 r0 = *(const f32x4*)(resid + off), r1 = *(const f32x4*)(resid + off + 4);
; #pragma unroll
;                     for (int e = 0; e < 4; ++e) { r0[e] += acc[ai][bj][m][0][e] * r2; r1[e] += acc[ai][bj][m][1][e] * r2; ss += r0[e] * r0[e] + r1[e] * r1[e]; }
;                     *(f32x4*)(hout + off) = r0; *(f32x4*)(hout + off + 4) = r1;
;                     u32x4 w; w.x = pk_bf16(r0[0], r0[1]); w.y = pk_bf16(r0[2], r0[3]); w.z = pk_bf16(r1[0], r1[1]); w.w = pk_bf16(r1[2], r1[3]);
;                     if (hb) *(u32x4*)(hb + off) = w;
;                 }
;                 ss += __shfl_xor(ss, 16); ss += __shfl_xor(ss, 32);
;                 if (fq == 0) __hip_atomic_fetch_add(sumsq_next + row, ss, __ATOMIC_RELAXED, __HIP_MEMORY_SCOPE_AGENT);
;                 asm volatile("" ::: "memory");
.LBB0_1517:
	s_or_b64 exec, exec, s[28:29]
	v_or_b32_e32 v82, 48, v146
	s_waitcnt lgkmcnt(0)
	v_ashrrev_i32_e32 v83, 31, v82
	v_lshl_add_u64 v[84:85], v[82:83], 2, s[14:15]
	global_load_dword v96, v[84:85], off
	v_lshlrev_b64 v[84:85], 10, v[82:83]
	v_lshl_add_u64 v[92:93], v[84:85], 0, v[148:149]
	v_lshl_add_u64 v[94:95], v[92:93], 2, s[8:9]
	global_load_dwordx4 v[84:87], v[94:95], off
	global_load_dwordx4 v[88:91], v[94:95], off offset:16
	v_lshlrev_b64 v[92:93], 1, v[92:93]
	s_waitcnt vmcnt(2)
	v_fmamk_f32 v98, v96, 0x3a800000, v158
	v_div_scale_f32 v99, s[0:1], v98, v98, 1.0
	v_rcp_f32_e32 v100, v99
	v_div_scale_f32 v101, vcc, 1.0, v98, 1.0
	v_lshl_add_u64 v[96:97], s[64:65], 0, v[92:93]
	v_fma_f32 v102, -v99, v100, 1.0
	v_fmac_f32_e32 v100, v102, v100
	v_mul_f32_e32 v102, v101, v100
	v_fma_f32 v103, -v99, v102, v101
	v_fmac_f32_e32 v102, v103, v100
	v_fma_f32 v99, -v99, v102, v101
	v_div_fmas_f32 v99, v99, v100, v102
	v_div_fixup_f32 v98, v99, v98, 1.0
	s_waitcnt vmcnt(1)
	v_pk_fma_f32 v[78:79], v[78:79], v[98:99], v[84:85] op_sel_hi:[1,0,1]
	s_waitcnt vmcnt(0)
	v_pk_fma_f32 v[74:75], v[74:75], v[98:99], v[88:89] op_sel_hi:[1,0,1]
	v_pk_fma_f32 v[80:81], v[80:81], v[98:99], v[86:87] op_sel_hi:[1,0,1]
	v_pk_fma_f32 v[76:77], v[76:77], v[98:99], v[90:91] op_sel_hi:[1,0,1]
	v_cvt_pk_bf16_f32 v84, v78, v79
	v_cvt_pk_bf16_f32 v85, v80, v81
	v_cvt_pk_bf16_f32 v86, v74, v75
	v_cvt_pk_bf16_f32 v87, v76, v77
	global_store_dwordx4 v[94:95], v[78:81], off
	global_store_dwordx4 v[94:95], v[74:77], off offset:16
	global_store_dwordx4 v[96:97], v[84:87], off
	global_load_dwordx4 v[84:87], v[94:95], off offset:512
	s_nop 0
	global_load_dwordx4 v[88:91], v[94:95], off offset:528
	v_pk_mul_f32 v[74:75], v[74:75], v[74:75]
	v_pk_mul_f32 v[76:77], v[76:77], v[76:77]
	v_pk_fma_f32 v[74:75], v[78:79], v[78:79], v[74:75]
	v_pk_fma_f32 v[76:77], v[80:81], v[80:81], v[76:77]
	v_add_f32_e32 v74, v74, v75
	v_add_f32_e32 v74, v76, v74
	v_add_f32_e32 v78, v77, v74
	v_or_b32_e32 v92, 0x100, v92
	s_waitcnt vmcnt(1)
	v_pk_fma_f32 v[70:71], v[70:71], v[98:99], v[84:85] op_sel_hi:[1,0,1]
	s_waitcnt vmcnt(0)
	v_pk_fma_f32 v[74:75], v[66:67], v[98:99], v[88:89] op_sel_hi:[1,0,1]
	v_pk_fma_f32 v[76:77], v[68:69], v[98:99], v[90:91] op_sel_hi:[1,0,1]
	v_pk_mul_f32 v[66:67], v[74:75], v[74:75]
	v_pk_fma_f32 v[72:73], v[72:73], v[98:99], v[86:87] op_sel_hi:[1,0,1]
	v_pk_fma_f32 v[66:67], v[70:71], v[70:71], v[66:67]
	v_pk_mul_f32 v[68:69], v[76:77], v[76:77]
	v_add_f32_e32 v66, v78, v66
	v_pk_fma_f32 v[68:69], v[72:73], v[72:73], v[68:69]
	v_add_f32_e32 v66, v67, v66
	v_add_f32_e32 v66, v68, v66
	v_add_f32_e32 v66, v69, v66
	v_mov_b32_e32 v67, v66
	s_nop 1
	v_permlane16_swap_b32_e32 v66, v67
	global_store_dwordx4 v[94:95], v[70:73], off offset:512
	v_lshl_add_u64 v[78:79], s[64:65], 0, v[92:93]
	v_cvt_pk_bf16_f32 v68, v70, v71
	v_cvt_pk_bf16_f32 v69, v72, v73
	s_waitcnt lgkmcnt(0)
	v_add_f32_e32 v66, v66, v67
	v_mov_b32_e32 v67, v66
	s_nop 1
	v_permlane32_swap_b32_e32 v66, v67
	v_cvt_pk_bf16_f32 v70, v74, v75
	v_cvt_pk_bf16_f32 v71, v76, v77
	global_store_dwordx4 v[94:95], v[74:77], off offset:528
	global_store_dwordx4 v[78:79], v[68:71], off
	s_and_saveexec_b64 s[28:29], s[2:3]
	s_cbranch_execz .LBB0_1519
	v_lshl_add_u64 v[68:69], v[82:83], 2, s[12:13]
	s_waitcnt lgkmcnt(0)
	v_add_f32_e32 v66, v66, v67
	global_atomic_add_f32 v[68:69], v66, off
.LBB0_1519:
	s_or_b64 exec, exec, s[28:29]
	global_load_dword v80, v[150:151], off offset:512
	v_add_u32_e32 v66, 0x80, v146
	s_waitcnt lgkmcnt(0)
	v_ashrrev_i32_e32 v67, 31, v66
	v_lshlrev_b64 v[68:69], 10, v[66:67]
	v_lshl_add_u64 v[76:77], v[68:69], 0, v[148:149]
	v_lshl_add_u64 v[78:79], v[76:77], 2, s[8:9]
	global_load_dwordx4 v[68:71], v[78:79], off
	global_load_dwordx4 v[72:75], v[78:79], off offset:16
	v_lshlrev_b64 v[76:77], 1, v[76:77]
	s_waitcnt vmcnt(2)
	v_fmamk_f32 v82, v80, 0x3a800000, v158
	v_div_scale_f32 v83, s[0:1], v82, v82, 1.0
	v_rcp_f32_e32 v84, v83
	v_div_scale_f32 v85, vcc, 1.0, v82, 1.0
	v_lshl_add_u64 v[80:81], s[64:65], 0, v[76:77]
	v_fma_f32 v86, -v83, v84, 1.0
	v_fmac_f32_e32 v84, v86, v84
	v_mul_f32_e32 v86, v85, v84
	v_fma_f32 v87, -v83, v86, v85
	v_fmac_f32_e32 v86, v87, v84
	v_fma_f32 v83, -v83, v86, v85
	v_div_fmas_f32 v83, v83, v84, v86
	v_div_fixup_f32 v82, v83, v82, 1.0
	s_waitcnt vmcnt(1)
	v_pk_fma_f32 v[62:63], v[62:63], v[82:83], v[68:69] op_sel_hi:[1,0,1]
	s_waitcnt vmcnt(0)
	v_pk_fma_f32 v[58:59], v[58:59], v[82:83], v[72:73] op_sel_hi:[1,0,1]
	v_pk_fma_f32 v[64:65], v[64:65], v[82:83], v[70:71] op_sel_hi:[1,0,1]
	v_pk_fma_f32 v[60:61], v[60:61], v[82:83], v[74:75] op_sel_hi:[1,0,1]
	v_cvt_pk_bf16_f32 v68, v62, v63
	v_cvt_pk_bf16_f32 v69, v64, v65
	v_cvt_pk_bf16_f32 v70, v58, v59
	v_cvt_pk_bf16_f32 v71, v60, v61
	global_store_dwordx4 v[78:79], v[62:65], off
	global_store_dwordx4 v[78:79], v[58:61], off offset:16
	global_store_dwordx4 v[80:81], v[68:71], off
	global_load_dwordx4 v[68:71], v[78:79], off offset:512
	s_nop 0
	global_load_dwordx4 v[72:75], v[78:79], off offset:528
	v_pk_mul_f32 v[58:59], v[58:59], v[58:59]
	v_pk_mul_f32 v[60:61], v[60:61], v[60:61]
	v_pk_fma_f32 v[58:59], v[62:63], v[62:63], v[58:59]
	v_pk_fma_f32 v[60:61], v[64:65], v[64:65], v[60:61]
	v_add_f32_e32 v58, v58, v59
	v_add_f32_e32 v58, v60, v58
	v_add_f32_e32 v62, v61, v58
	v_or_b32_e32 v76, 0x100, v76
	s_waitcnt vmcnt(1)
	v_pk_fma_f32 v[54:55], v[54:55], v[82:83], v[68:69] op_sel_hi:[1,0,1]
	s_waitcnt vmcnt(0)
	v_pk_fma_f32 v[58:59], v[50:51], v[82:83], v[72:73] op_sel_hi:[1,0,1]
	v_pk_fma_f32 v[60:61], v[52:53], v[82:83], v[74:75] op_sel_hi:[1,0,1]
	v_pk_mul_f32 v[50:51], v[58:59], v[58:59]
	v_pk_fma_f32 v[56:57], v[56:57], v[82:83], v[70:71] op_sel_hi:[1,0,1]
	v_pk_fma_f32 v[50:51], v[54:55], v[54:55], v[50:51]
	v_pk_mul_f32 v[52:53], v[60:61], v[60:61]
	v_add_f32_e32 v50, v62, v50
	v_pk_fma_f32 v[52:53], v[56:57], v[56:57], v[52:53]
	v_add_f32_e32 v50, v51, v50
	v_add_f32_e32 v50, v52, v50
	v_add_f32_e32 v50, v53, v50
	v_mov_b32_e32 v51, v50
	s_nop 1
	v_permlane16_swap_b32_e32 v50, v51
	global_store_dwordx4 v[78:79], v[54:57], off offset:512
	v_lshl_add_u64 v[62:63], s[64:65], 0, v[76:77]
	v_cvt_pk_bf16_f32 v52, v54, v55
	v_cvt_pk_bf16_f32 v53, v56, v57
	s_waitcnt lgkmcnt(0)
	v_add_f32_e32 v50, v50, v51
	v_mov_b32_e32 v51, v50
	s_nop 1
	v_permlane32_swap_b32_e32 v50, v51
	v_cvt_pk_bf16_f32 v54, v58, v59
	v_cvt_pk_bf16_f32 v55, v60, v61
	global_store_dwordx4 v[78:79], v[58:61], off offset:528
	global_store_dwordx4 v[62:63], v[52:55], off
	s_and_saveexec_b64 s[28:29], s[2:3]
	s_cbranch_execz .LBB0_1521
	v_lshl_add_u64 v[52:53], v[66:67], 2, s[12:13]
	s_waitcnt lgkmcnt(0)
	v_add_f32_e32 v50, v50, v51
	global_atomic_add_f32 v[52:53], v50, off
; DI unsigned pk_bf16(float a, float b) { f32x2 v = {a, b}; bf2_t r = __builtin_convertvector(v, bf2_t); return __builtin_bit_cast(unsigned, r); }
;     DI void operator()(const pg8::f32x4 (&acc)[2][2][4][2], const pg8::Unit& u, int wr, int wc, int fr, int fq) const {
;     ...
;                 const int row = row0 + ai * 128 + m * 16; float ss = 0.f;
;                 const float r2 = sumsq_in ? 1.0f / (sumsq_in[row] * (1.0f / 1024.0f) + EPS) : 1.0f;
; #pragma unroll
;                 for (int bj = 0; bj < 2; ++bj) {
;                     const size_t off = (size_t)row * 1024 + col0 + bj * 128;
;                     f32x4 r0 = *(const f32x4*)(resid + off), r1 = *(const f32x4*)(resid + off + 4);
; #pragma unroll
;                     for (int e = 0; e < 4; ++e) { r0[e] += acc[ai][bj][m][0][e] * r2; r1[e] += acc[ai][bj][m][1][e] * r2; ss += r0[e] * r0[e] + r1[e] * r1[e]; }
;                     *(f32x4*)(hout + off) = r0; *(f32x4*)(hout + off + 4) = r1;
;                     u32x4 w; w.x = pk_bf16(r0[0], r0[1]); w.y = pk_bf16(r0[2], r0[3]); w.z = pk_bf16(r1[0], r1[1]); w.w = pk_bf16(r1[2], r1[3]);
;                     if (hb) *(u32x4*)(hb + off) = w;
;                 }
;                 ss += __shfl_xor(ss, 16); ss += __shfl_xor(ss, 32);
;                 if (fq == 0) __hip_atomic_fetch_add(sumsq_next + row, ss, __ATOMIC_RELAXED, __HIP_MEMORY_SCOPE_AGENT);
;                 asm volatile("" ::: "memory");
.LBB0_1521:
	s_or_b64 exec, exec, s[28:29]
	global_load_dword v64, v[150:151], off offset:576
	v_add_u32_e32 v50, 0x90, v146
	s_waitcnt lgkmcnt(0)
	v_ashrrev_i32_e32 v51, 31, v50
	v_lshlrev_b64 v[52:53], 10, v[50:51]
	v_lshl_add_u64 v[60:61], v[52:53], 0, v[148:149]
	v_lshl_add_u64 v[62:63], v[60:61], 2, s[8:9]
	global_load_dwordx4 v[52:55], v[62:63], off
	global_load_dwordx4 v[56:59], v[62:63], off offset:16
	v_lshlrev_b64 v[60:61], 1, v[60:61]
	s_waitcnt vmcnt(2)
	v_fmamk_f32 v66, v64, 0x3a800000, v158
	v_div_scale_f32 v67, s[0:1], v66, v66, 1.0
	v_rcp_f32_e32 v68, v67
	v_div_scale_f32 v69, vcc, 1.0, v66, 1.0
	v_lshl_add_u64 v[64:65], s[64:65], 0, v[60:61]
	v_fma_f32 v70, -v67, v68, 1.0
	v_fmac_f32_e32 v68, v70, v68
	v_mul_f32_e32 v70, v69, v68
	v_fma_f32 v71, -v67, v70, v69
	v_fmac_f32_e32 v70, v71, v68
	v_fma_f32 v67, -v67, v70, v69
	v_div_fmas_f32 v67, v67, v68, v70
	v_div_fixup_f32 v66, v67, v66, 1.0
	s_waitcnt vmcnt(1)
	v_pk_fma_f32 v[46:47], v[46:47], v[66:67], v[52:53] op_sel_hi:[1,0,1]
	s_waitcnt vmcnt(0)
	v_pk_fma_f32 v[42:43], v[42:43], v[66:67], v[56:57] op_sel_hi:[1,0,1]
	v_pk_fma_f32 v[48:49], v[48:49], v[66:67], v[54:55] op_sel_hi:[1,0,1]
	v_pk_fma_f32 v[44:45], v[44:45], v[66:67], v[58:59] op_sel_hi:[1,0,1]
	v_cvt_pk_bf16_f32 v52, v46, v47
	v_cvt_pk_bf16_f32 v53, v48, v49
	v_cvt_pk_bf16_f32 v54, v42, v43
	v_cvt_pk_bf16_f32 v55, v44, v45
	global_store_dwordx4 v[62:63], v[46:49], off
	global_store_dwordx4 v[62:63], v[42:45], off offset:16
	global_store_dwordx4 v[64:65], v[52:55], off
	global_load_dwordx4 v[52:55], v[62:63], off offset:512
	s_nop 0
	global_load_dwordx4 v[56:59], v[62:63], off offset:528
	v_pk_mul_f32 v[42:43], v[42:43], v[42:43]
	v_pk_mul_f32 v[44:45], v[44:45], v[44:45]
	v_pk_fma_f32 v[42:43], v[46:47], v[46:47], v[42:43]
	v_pk_fma_f32 v[44:45], v[48:49], v[48:49], v[44:45]
	v_add_f32_e32 v42, v42, v43
	v_add_f32_e32 v42, v44, v42
	v_add_f32_e32 v46, v45, v42
	v_or_b32_e32 v60, 0x100, v60
	s_waitcnt vmcnt(1)
	v_pk_fma_f32 v[38:39], v[38:39], v[66:67], v[52:53] op_sel_hi:[1,0,1]
	s_waitcnt vmcnt(0)
	v_pk_fma_f32 v[42:43], v[34:35], v[66:67], v[56:57] op_sel_hi:[1,0,1]
	v_pk_fma_f32 v[44:45], v[36:37], v[66:67], v[58:59] op_sel_hi:[1,0,1]
	v_pk_mul_f32 v[34:35], v[42:43], v[42:43]
	v_pk_fma_f32 v[40:41], v[40:41], v[66:67], v[54:55] op_sel_hi:[1,0,1]
	v_pk_fma_f32 v[34:35], v[38:39], v[38:39], v[34:35]
	v_pk_mul_f32 v[36:37], v[44:45], v[44:45]
	v_add_f32_e32 v34, v46, v34
	v_pk_fma_f32 v[36:37], v[40:41], v[40:41], v[36:37]
	v_add_f32_e32 v34, v35, v34
	v_add_f32_e32 v34, v36, v34
	v_add_f32_e32 v34, v37, v34
	v_mov_b32_e32 v35, v34
	s_nop 1
	v_permlane16_swap_b32_e32 v34, v35
	global_store_dwordx4 v[62:63], v[38:41], off offset:512
	v_lshl_add_u64 v[46:47], s[64:65], 0, v[60:61]
	v_cvt_pk_bf16_f32 v36, v38, v39
	v_cvt_pk_bf16_f32 v37, v40, v41
	s_waitcnt lgkmcnt(0)
	v_add_f32_e32 v34, v34, v35
	v_mov_b32_e32 v35, v34
	s_nop 1
	v_permlane32_swap_b32_e32 v34, v35
	v_cvt_pk_bf16_f32 v38, v42, v43
	v_cvt_pk_bf16_f32 v39, v44, v45
	global_store_dwordx4 v[62:63], v[42:45], off offset:528
	global_store_dwordx4 v[46:47], v[36:39], off
	s_and_saveexec_b64 s[28:29], s[2:3]
	s_cbranch_execz .LBB0_1523
	v_lshl_add_u64 v[36:37], v[50:51], 2, s[12:13]
	s_waitcnt lgkmcnt(0)
	v_add_f32_e32 v34, v34, v35
	global_atomic_add_f32 v[36:37], v34, off
; DI unsigned pk_bf16(float a, float b) { f32x2 v = {a, b}; bf2_t r = __builtin_convertvector(v, bf2_t); return __builtin_bit_cast(unsigned, r); }
;     DI void operator()(const pg8::f32x4 (&acc)[2][2][4][2], const pg8::Unit& u, int wr, int wc, int fr, int fq) const {
;     ...
;                 const int row = row0 + ai * 128 + m * 16; float ss = 0.f;
;                 const float r2 = sumsq_in ? 1.0f / (sumsq_in[row] * (1.0f / 1024.0f) + EPS) : 1.0f;
; #pragma unroll
;                 for (int bj = 0; bj < 2; ++bj) {
;                     const size_t off = (size_t)row * 1024 + col0 + bj * 128;
;                     f32x4 r0 = *(const f32x4*)(resid + off), r1 = *(const f32x4*)(resid + off + 4);
; #pragma unroll
;                     for (int e = 0; e < 4; ++e) { r0[e] += acc[ai][bj][m][0][e] * r2; r1[e] += acc[ai][bj][m][1][e] * r2; ss += r0[e] * r0[e] + r1[e] * r1[e]; }
;                     *(f32x4*)(hout + off) = r0; *(f32x4*)(hout + off + 4) = r1;
;                     u32x4 w; w.x = pk_bf16(r0[0], r0[1]); w.y = pk_bf16(r0[2], r0[3]); w.z = pk_bf16(r1[0], r1[1]); w.w = pk_bf16(r1[2], r1[3]);
;                     if (hb) *(u32x4*)(hb + off) = w;
;                 }
;                 ss += __shfl_xor(ss, 16); ss += __shfl_xor(ss, 32);
;                 if (fq == 0) __hip_atomic_fetch_add(sumsq_next + row, ss, __ATOMIC_RELAXED, __HIP_MEMORY_SCOPE_AGENT);
;                 asm volatile("" ::: "memory");
.LBB0_1523:
	s_or_b64 exec, exec, s[28:29]
	global_load_dword v48, v[150:151], off offset:640
	v_add_u32_e32 v34, 0xa0, v146
	s_waitcnt lgkmcnt(0)
	v_ashrrev_i32_e32 v35, 31, v34
	v_lshlrev_b64 v[36:37], 10, v[34:35]
	v_lshl_add_u64 v[44:45], v[36:37], 0, v[148:149]
	v_lshl_add_u64 v[46:47], v[44:45], 2, s[8:9]
	global_load_dwordx4 v[36:39], v[46:47], off
	global_load_dwordx4 v[40:43], v[46:47], off offset:16
	v_lshlrev_b64 v[44:45], 1, v[44:45]
	s_waitcnt vmcnt(2)
	v_fmamk_f32 v50, v48, 0x3a800000, v158
	v_div_scale_f32 v51, s[0:1], v50, v50, 1.0
	v_rcp_f32_e32 v52, v51
	v_div_scale_f32 v53, vcc, 1.0, v50, 1.0
	v_lshl_add_u64 v[48:49], s[64:65], 0, v[44:45]
	v_fma_f32 v54, -v51, v52, 1.0
	v_fmac_f32_e32 v52, v54, v52
	v_mul_f32_e32 v54, v53, v52
	v_fma_f32 v55, -v51, v54, v53
	v_fmac_f32_e32 v54, v55, v52
	v_fma_f32 v51, -v51, v54, v53
	v_div_fmas_f32 v51, v51, v52, v54
	v_div_fixup_f32 v50, v51, v50, 1.0
	s_waitcnt vmcnt(1)
	v_pk_fma_f32 v[30:31], v[30:31], v[50:51], v[36:37] op_sel_hi:[1,0,1]
	s_waitcnt vmcnt(0)
	v_pk_fma_f32 v[26:27], v[26:27], v[50:51], v[40:41] op_sel_hi:[1,0,1]
	v_pk_fma_f32 v[32:33], v[32:33], v[50:51], v[38:39] op_sel_hi:[1,0,1]
	v_pk_fma_f32 v[28:29], v[28:29], v[50:51], v[42:43] op_sel_hi:[1,0,1]
	v_cvt_pk_bf16_f32 v36, v30, v31
	v_cvt_pk_bf16_f32 v37, v32, v33
	v_cvt_pk_bf16_f32 v38, v26, v27
	v_cvt_pk_bf16_f32 v39, v28, v29
	global_store_dwordx4 v[46:47], v[30:33], off
	global_store_dwordx4 v[46:47], v[26:29], off offset:16
	global_store_dwordx4 v[48:49], v[36:39], off
	global_load_dwordx4 v[36:39], v[46:47], off offset:512
	s_nop 0
	global_load_dwordx4 v[40:43], v[46:47], off offset:528
	v_pk_mul_f32 v[26:27], v[26:27], v[26:27]
	v_pk_mul_f32 v[28:29], v[28:29], v[28:29]
	v_pk_fma_f32 v[26:27], v[30:31], v[30:31], v[26:27]
	v_pk_fma_f32 v[28:29], v[32:33], v[32:33], v[28:29]
	v_add_f32_e32 v26, v26, v27
	v_add_f32_e32 v26, v28, v26
	v_add_f32_e32 v30, v29, v26
	v_or_b32_e32 v44, 0x100, v44
	s_waitcnt vmcnt(1)
	v_pk_fma_f32 v[22:23], v[22:23], v[50:51], v[36:37] op_sel_hi:[1,0,1]
	s_waitcnt vmcnt(0)
	v_pk_fma_f32 v[26:27], v[18:19], v[50:51], v[40:41] op_sel_hi:[1,0,1]
	v_pk_fma_f32 v[28:29], v[20:21], v[50:51], v[42:43] op_sel_hi:[1,0,1]
	v_pk_mul_f32 v[18:19], v[26:27], v[26:27]
	v_pk_fma_f32 v[24:25], v[24:25], v[50:51], v[38:39] op_sel_hi:[1,0,1]
	v_pk_fma_f32 v[18:19], v[22:23], v[22:23], v[18:19]
	v_pk_mul_f32 v[20:21], v[28:29], v[28:29]
	v_add_f32_e32 v18, v30, v18
	v_pk_fma_f32 v[20:21], v[24:25], v[24:25], v[20:21]
	v_add_f32_e32 v18, v19, v18
	v_add_f32_e32 v18, v20, v18
	v_add_f32_e32 v18, v21, v18
	v_mov_b32_e32 v19, v18
	s_nop 1
	v_permlane16_swap_b32_e32 v18, v19
	global_store_dwordx4 v[46:47], v[22:25], off offset:512
	v_lshl_add_u64 v[30:31], s[64:65], 0, v[44:45]
	v_cvt_pk_bf16_f32 v20, v22, v23
	v_cvt_pk_bf16_f32 v21, v24, v25
	s_waitcnt lgkmcnt(0)
	v_add_f32_e32 v18, v18, v19
	v_mov_b32_e32 v19, v18
	s_nop 1
	v_permlane32_swap_b32_e32 v18, v19
	v_cvt_pk_bf16_f32 v22, v26, v27
	v_cvt_pk_bf16_f32 v23, v28, v29
	global_store_dwordx4 v[46:47], v[26:29], off offset:528
	global_store_dwordx4 v[30:31], v[20:23], off
	s_and_saveexec_b64 s[28:29], s[2:3]
	s_cbranch_execz .LBB0_1525
	v_lshl_add_u64 v[20:21], v[34:35], 2, s[12:13]
	s_waitcnt lgkmcnt(0)
	v_add_f32_e32 v18, v18, v19
	global_atomic_add_f32 v[20:21], v18, off
.LBB0_1525:
	s_or_b64 exec, exec, s[28:29]
	global_load_dword v32, v[150:151], off offset:704
	v_add_u32_e32 v18, 0xb0, v146
	s_waitcnt lgkmcnt(0)
	v_ashrrev_i32_e32 v19, 31, v18
	v_lshlrev_b64 v[20:21], 10, v[18:19]
	v_lshl_add_u64 v[28:29], v[20:21], 0, v[148:149]
	v_lshl_add_u64 v[30:31], v[28:29], 2, s[8:9]
	global_load_dwordx4 v[20:23], v[30:31], off
	global_load_dwordx4 v[24:27], v[30:31], off offset:16
	v_lshlrev_b64 v[28:29], 1, v[28:29]
	s_waitcnt vmcnt(2)
	v_fmamk_f32 v34, v32, 0x3a800000, v158
	v_div_scale_f32 v35, s[0:1], v34, v34, 1.0
	v_rcp_f32_e32 v36, v35
	v_div_scale_f32 v37, vcc, 1.0, v34, 1.0
	v_lshl_add_u64 v[32:33], s[64:65], 0, v[28:29]
	v_fma_f32 v38, -v35, v36, 1.0
	v_fmac_f32_e32 v36, v38, v36
	v_mul_f32_e32 v38, v37, v36
	v_fma_f32 v39, -v35, v38, v37
	v_fmac_f32_e32 v38, v39, v36
	v_fma_f32 v35, -v35, v38, v37
	v_div_fmas_f32 v35, v35, v36, v38
	v_div_fixup_f32 v34, v35, v34, 1.0
	s_waitcnt vmcnt(1)
	v_pk_fma_f32 v[14:15], v[14:15], v[34:35], v[20:21] op_sel_hi:[1,0,1]
	s_waitcnt vmcnt(0)
	v_pk_fma_f32 v[10:11], v[10:11], v[34:35], v[24:25] op_sel_hi:[1,0,1]
	v_pk_fma_f32 v[16:17], v[16:17], v[34:35], v[22:23] op_sel_hi:[1,0,1]
	v_pk_fma_f32 v[12:13], v[12:13], v[34:35], v[26:27] op_sel_hi:[1,0,1]
	v_cvt_pk_bf16_f32 v20, v14, v15
	v_cvt_pk_bf16_f32 v21, v16, v17
	v_cvt_pk_bf16_f32 v22, v10, v11
	v_cvt_pk_bf16_f32 v23, v12, v13
	global_store_dwordx4 v[30:31], v[14:17], off
	global_store_dwordx4 v[30:31], v[10:13], off offset:16
	global_store_dwordx4 v[32:33], v[20:23], off
	global_load_dwordx4 v[20:23], v[30:31], off offset:512
	s_nop 0
	global_load_dwordx4 v[24:27], v[30:31], off offset:528
	v_pk_mul_f32 v[10:11], v[10:11], v[10:11]
	v_pk_mul_f32 v[12:13], v[12:13], v[12:13]
	v_pk_fma_f32 v[10:11], v[14:15], v[14:15], v[10:11]
	v_pk_fma_f32 v[12:13], v[16:17], v[16:17], v[12:13]
	v_add_f32_e32 v10, v10, v11
	v_add_f32_e32 v10, v12, v10
	v_add_f32_e32 v14, v13, v10
	v_or_b32_e32 v28, 0x100, v28
	s_waitcnt vmcnt(1)
	v_pk_fma_f32 v[6:7], v[6:7], v[34:35], v[20:21] op_sel_hi:[1,0,1]
	s_waitcnt vmcnt(0)
	v_pk_fma_f32 v[10:11], v[2:3], v[34:35], v[24:25] op_sel_hi:[1,0,1]
	v_pk_fma_f32 v[12:13], v[4:5], v[34:35], v[26:27] op_sel_hi:[1,0,1]
	v_pk_mul_f32 v[2:3], v[10:11], v[10:11]
	v_pk_fma_f32 v[8:9], v[8:9], v[34:35], v[22:23] op_sel_hi:[1,0,1]
	v_pk_fma_f32 v[2:3], v[6:7], v[6:7], v[2:3]
	v_pk_mul_f32 v[4:5], v[12:13], v[12:13]
	v_add_f32_e32 v2, v14, v2
	v_pk_fma_f32 v[4:5], v[8:9], v[8:9], v[4:5]
	v_add_f32_e32 v2, v3, v2
	v_add_f32_e32 v2, v4, v2
	v_add_f32_e32 v2, v5, v2
	v_mov_b32_e32 v3, v2
	s_nop 1
	v_permlane16_swap_b32_e32 v2, v3
	global_store_dwordx4 v[30:31], v[6:9], off offset:512
	v_lshl_add_u64 v[14:15], s[64:65], 0, v[28:29]
	v_cvt_pk_bf16_f32 v4, v6, v7
	v_cvt_pk_bf16_f32 v5, v8, v9
	s_waitcnt lgkmcnt(0)
	v_add_f32_e32 v2, v2, v3
	v_mov_b32_e32 v3, v2
	s_nop 1
	v_permlane32_swap_b32_e32 v2, v3
	v_cvt_pk_bf16_f32 v6, v10, v11
	v_cvt_pk_bf16_f32 v7, v12, v13
	global_store_dwordx4 v[30:31], v[10:13], off offset:528
	global_store_dwordx4 v[14:15], v[4:7], off
	s_and_saveexec_b64 s[28:29], s[2:3]
	s_cbranch_execz .LBB0_1527
	v_lshl_add_u64 v[4:5], v[18:19], 2, s[12:13]
	s_waitcnt lgkmcnt(0)
	v_add_f32_e32 v2, v2, v3
	global_atomic_add_f32 v[4:5], v2, off

; DI unsigned pk_bf16(float a, float b) { f32x2 v = {a, b}; bf2_t r = __builtin_convertvector(v, bf2_t); return __builtin_bit_cast(unsigned, r); }
;     DI void operator()(const pg8::f32x4 (&acc)[2][2][4][2], const pg8::Unit& u, int wr, int wc, int fr, int fq) const {
;     ...
;                 const int row = row0 + ai * 128 + m * 16; float ss = 0.f;
;                 const float r2 = sumsq_in ? 1.0f / (sumsq_in[row] * (1.0f / 1024.0f) + EPS) : 1.0f;
; #pragma unroll
;                 for (int bj = 0; bj < 2; ++bj) {
;                     const size_t off = (size_t)row * 1024 + col0 + bj * 128;
;                     f32x4 r0 = *(const f32x4*)(resid + off), r1 = *(const f32x4*)(resid + off + 4);
; #pragma unroll
;                     for (int e = 0; e < 4; ++e) { r0[e] += acc[ai][bj][m][0][e] * r2; r1[e] += acc[ai][bj][m][1][e] * r2; ss += r0[e] * r0[e] + r1[e] * r1[e]; }
;                     *(f32x4*)(hout + off) = r0; *(f32x4*)(hout + off + 4) = r1;
;                     u32x4 w; w.x = pk_bf16(r0[0], r0[1]); w.y = pk_bf16(r0[2], r0[3]); w.z = pk_bf16(r1[0], r1[1]); w.w = pk_bf16(r1[2], r1[3]);
;                     if (hb) *(u32x4*)(hb + off) = w;
;                 }
;                 ss += __shfl_xor(ss, 16); ss += __shfl_xor(ss, 32);
;                 if (fq == 0) __hip_atomic_fetch_add(sumsq_next + row, ss, __ATOMIC_RELAXED, __HIP_MEMORY_SCOPE_AGENT);
;                 asm volatile("" ::: "memory");
.LBB0_3676:
	v_lshl_add_u32 v148, s26, 8, v1
	v_lshl_or_b32 v146, s28, 8, v151
	v_ashrrev_i32_e32 v149, 31, v148
	v_ashrrev_i32_e32 v147, 31, v146
	v_lshlrev_b64 v[156:157], 10, v[148:149]
	v_lshl_add_u64 v[164:165], v[156:157], 0, v[146:147]
	v_lshl_add_u64 v[168:169], v[164:165], 2, s[8:9]
	global_load_dwordx4 v[156:159], v[168:169], off
	global_load_dwordx4 v[160:163], v[168:169], off offset:16
	v_lshlrev_b64 v[170:171], 1, v[164:165]
	v_lshl_add_u64 v[164:165], s[64:65], 0, v[170:171]
	v_or_b32_e32 v170, 0x100, v170
	s_waitcnt vmcnt(0)
	v_pk_add_f32 v[128:129], v[128:129], v[158:159]
	v_pk_add_f32 v[126:127], v[126:127], v[156:157]
	v_pk_add_f32 v[158:159], v[124:125], v[162:163]
	v_pk_add_f32 v[156:157], v[122:123], v[160:161]
	v_cvt_pk_bf16_f32 v122, v126, v127
	v_cvt_pk_bf16_f32 v123, v128, v129
	v_cvt_pk_bf16_f32 v124, v156, v157
	v_cvt_pk_bf16_f32 v125, v158, v159
	global_store_dwordx4 v[168:169], v[126:129], off
	global_store_dwordx4 v[168:169], v[156:159], off offset:16
	global_store_dwordx4 v[164:165], v[122:125], off
	global_load_dwordx4 v[160:163], v[168:169], off offset:512
	s_nop 0
	global_load_dwordx4 v[164:167], v[168:169], off offset:528
	v_and_b32_e32 v123, 64, v155
	v_xor_b32_e32 v122, 16, v155
	v_add_u32_e32 v123, 64, v123
	v_xor_b32_e32 v124, 32, v155
	v_cmp_lt_i32_e32 vcc, v122, v123
	v_pk_mul_f32 v[156:157], v[156:157], v[156:157]
	s_waitcnt vmcnt(1)
	v_pk_add_f32 v[118:119], v[118:119], v[160:161]
	v_cndmask_b32_e32 v122, v155, v122, vcc
	v_cmp_lt_i32_e32 vcc, v124, v123
	v_lshlrev_b32_e32 v123, 2, v122
	v_pk_fma_f32 v[126:127], v[126:127], v[126:127], v[156:157]
	v_cndmask_b32_e32 v124, v155, v124, vcc
	v_lshlrev_b32_e32 v122, 2, v124
	v_pk_mul_f32 v[124:125], v[158:159], v[158:159]
	v_add_f32_e32 v126, v126, v127
	v_pk_fma_f32 v[124:125], v[128:129], v[128:129], v[124:125]
	v_pk_add_f32 v[120:121], v[120:121], v[162:163]
	v_add_f32_e32 v124, v124, v126
	v_add_f32_e32 v128, v125, v124
	s_waitcnt vmcnt(0)
	v_pk_add_f32 v[124:125], v[114:115], v[164:165]
	v_pk_add_f32 v[126:127], v[116:117], v[166:167]
	v_pk_mul_f32 v[116:117], v[124:125], v[124:125]
	v_pk_mul_f32 v[114:115], v[126:127], v[126:127]
	v_pk_fma_f32 v[116:117], v[118:119], v[118:119], v[116:117]
	v_pk_fma_f32 v[114:115], v[120:121], v[120:121], v[114:115]
	v_add_f32_e32 v116, v128, v116
	v_add_f32_e32 v116, v117, v116
	v_add_f32_e32 v114, v114, v116
	v_add_f32_e32 v114, v115, v114
	v_mov_b32_e32 v115, v114
	s_nop 1
	v_permlane16_swap_b32_e32 v114, v115
	global_store_dwordx4 v[168:169], v[118:121], off offset:512
	v_lshl_add_u64 v[128:129], s[64:65], 0, v[170:171]
	v_cvt_pk_bf16_f32 v116, v118, v119
	v_cvt_pk_bf16_f32 v117, v120, v121
	s_waitcnt lgkmcnt(0)
	v_add_f32_e32 v114, v114, v115
	v_mov_b32_e32 v115, v114
	s_nop 1
	v_permlane32_swap_b32_e32 v114, v115
	v_cvt_pk_bf16_f32 v118, v124, v125
	v_cvt_pk_bf16_f32 v119, v126, v127
	global_store_dwordx4 v[168:169], v[124:127], off offset:528
	global_store_dwordx4 v[128:129], v[116:119], off
	s_and_saveexec_b64 s[26:27], s[2:3]
	s_cbranch_execz .LBB0_3678
	v_lshl_add_u64 v[116:117], v[148:149], 2, s[12:13]
	s_waitcnt lgkmcnt(0)
	v_add_f32_e32 v114, v114, v115
	global_atomic_add_f32 v[116:117], v114, off
.LBB0_3678:
	s_or_b64 exec, exec, s[26:27]
	v_or_b32_e32 v114, 16, v148
	s_waitcnt lgkmcnt(0)
	v_ashrrev_i32_e32 v115, 31, v114
	v_lshlrev_b64 v[116:117], 10, v[114:115]
	v_lshl_add_u64 v[120:121], v[116:117], 0, v[146:147]
	v_lshl_add_u64 v[128:129], v[120:121], 2, s[8:9]
	global_load_dwordx4 v[116:119], v[128:129], off
	global_load_dwordx4 v[124:127], v[128:129], off offset:16
	v_lshlrev_b64 v[120:121], 1, v[120:121]
	v_lshl_add_u64 v[156:157], s[64:65], 0, v[120:121]
	v_or_b32_e32 v120, 0x100, v120
	s_waitcnt vmcnt(1)
	v_pk_add_f32 v[112:113], v[112:113], v[118:119]
	v_pk_add_f32 v[110:111], v[110:111], v[116:117]
	s_waitcnt vmcnt(0)
	v_pk_add_f32 v[108:109], v[108:109], v[126:127]
	v_pk_add_f32 v[106:107], v[106:107], v[124:125]
	v_cvt_pk_bf16_f32 v116, v110, v111
	v_cvt_pk_bf16_f32 v117, v112, v113
	v_cvt_pk_bf16_f32 v118, v106, v107
	v_cvt_pk_bf16_f32 v119, v108, v109
	global_store_dwordx4 v[128:129], v[110:113], off
	global_store_dwordx4 v[128:129], v[106:109], off offset:16
	global_store_dwordx4 v[156:157], v[116:119], off
	global_load_dwordx4 v[116:119], v[128:129], off offset:512
	s_nop 0
	global_load_dwordx4 v[124:127], v[128:129], off offset:528
	v_pk_mul_f32 v[106:107], v[106:107], v[106:107]
	v_pk_mul_f32 v[108:109], v[108:109], v[108:109]
	v_pk_fma_f32 v[106:107], v[110:111], v[110:111], v[106:107]
	v_pk_fma_f32 v[108:109], v[112:113], v[112:113], v[108:109]
	v_add_f32_e32 v106, v106, v107
	v_add_f32_e32 v106, v108, v106
	v_add_f32_e32 v110, v109, v106
	s_waitcnt vmcnt(1)
	v_pk_add_f32 v[102:103], v[102:103], v[116:117]
	s_waitcnt vmcnt(0)
	v_pk_add_f32 v[106:107], v[98:99], v[124:125]
	v_pk_add_f32 v[108:109], v[100:101], v[126:127]
	v_pk_mul_f32 v[100:101], v[106:107], v[106:107]
	v_pk_add_f32 v[104:105], v[104:105], v[118:119]
	v_pk_fma_f32 v[100:101], v[102:103], v[102:103], v[100:101]
	v_pk_mul_f32 v[98:99], v[108:109], v[108:109]
	v_add_f32_e32 v100, v110, v100
	v_pk_fma_f32 v[98:99], v[104:105], v[104:105], v[98:99]
	v_add_f32_e32 v100, v101, v100
	v_add_f32_e32 v98, v98, v100
	v_add_f32_e32 v98, v99, v98
	v_mov_b32_e32 v99, v98
	s_nop 1
	v_permlane16_swap_b32_e32 v98, v99
	global_store_dwordx4 v[128:129], v[102:105], off offset:512
	v_lshl_add_u64 v[110:111], s[64:65], 0, v[120:121]
	v_cvt_pk_bf16_f32 v100, v102, v103
	v_cvt_pk_bf16_f32 v101, v104, v105
	s_waitcnt lgkmcnt(0)
	v_add_f32_e32 v98, v98, v99
	v_mov_b32_e32 v99, v98
	s_nop 1
	v_permlane32_swap_b32_e32 v98, v99
	v_cvt_pk_bf16_f32 v102, v106, v107
	v_cvt_pk_bf16_f32 v103, v108, v109
	global_store_dwordx4 v[128:129], v[106:109], off offset:528
	global_store_dwordx4 v[110:111], v[100:103], off
	s_and_saveexec_b64 s[26:27], s[2:3]
	s_cbranch_execz .LBB0_3680
	v_lshl_add_u64 v[100:101], v[114:115], 2, s[12:13]
	s_waitcnt lgkmcnt(0)
	v_add_f32_e32 v98, v98, v99
	global_atomic_add_f32 v[100:101], v98, off
; DI unsigned pk_bf16(float a, float b) { f32x2 v = {a, b}; bf2_t r = __builtin_convertvector(v, bf2_t); return __builtin_bit_cast(unsigned, r); }
;     DI void operator()(const pg8::f32x4 (&acc)[2][2][4][2], const pg8::Unit& u, int wr, int wc, int fr, int fq) const {
;     ...
;                 const int row = row0 + ai * 128 + m * 16; float ss = 0.f;
;                 const float r2 = sumsq_in ? 1.0f / (sumsq_in[row] * (1.0f / 1024.0f) + EPS) : 1.0f;
; #pragma unroll
;                 for (int bj = 0; bj < 2; ++bj) {
;                     const size_t off = (size_t)row * 1024 + col0 + bj * 128;
;                     f32x4 r0 = *(const f32x4*)(resid + off), r1 = *(const f32x4*)(resid + off + 4);
; #pragma unroll
;                     for (int e = 0; e < 4; ++e) { r0[e] += acc[ai][bj][m][0][e] * r2; r1[e] += acc[ai][bj][m][1][e] * r2; ss += r0[e] * r0[e] + r1[e] * r1[e]; }
;                     *(f32x4*)(hout + off) = r0; *(f32x4*)(hout + off + 4) = r1;
;                     u32x4 w; w.x = pk_bf16(r0[0], r0[1]); w.y = pk_bf16(r0[2], r0[3]); w.z = pk_bf16(r1[0], r1[1]); w.w = pk_bf16(r1[2], r1[3]);
;                     if (hb) *(u32x4*)(hb + off) = w;
;                 }
;                 ss += __shfl_xor(ss, 16); ss += __shfl_xor(ss, 32);
;                 if (fq == 0) __hip_atomic_fetch_add(sumsq_next + row, ss, __ATOMIC_RELAXED, __HIP_MEMORY_SCOPE_AGENT);
;                 asm volatile("" ::: "memory");
.LBB0_3680:
	s_or_b64 exec, exec, s[26:27]
	v_or_b32_e32 v98, 32, v148
	s_waitcnt lgkmcnt(0)
	v_ashrrev_i32_e32 v99, 31, v98
	v_lshlrev_b64 v[100:101], 10, v[98:99]
	v_lshl_add_u64 v[108:109], v[100:101], 0, v[146:147]
	v_lshl_add_u64 v[110:111], v[108:109], 2, s[8:9]
	global_load_dwordx4 v[100:103], v[110:111], off
	global_load_dwordx4 v[104:107], v[110:111], off offset:16
	v_lshlrev_b64 v[108:109], 1, v[108:109]
	v_lshl_add_u64 v[112:113], s[64:65], 0, v[108:109]
	v_or_b32_e32 v108, 0x100, v108
	s_waitcnt vmcnt(1)
	v_pk_add_f32 v[96:97], v[96:97], v[102:103]
	v_pk_add_f32 v[94:95], v[94:95], v[100:101]
	s_waitcnt vmcnt(0)
	v_pk_add_f32 v[92:93], v[92:93], v[106:107]
	v_pk_add_f32 v[90:91], v[90:91], v[104:105]
	v_cvt_pk_bf16_f32 v100, v94, v95
	v_cvt_pk_bf16_f32 v101, v96, v97
	v_cvt_pk_bf16_f32 v102, v90, v91
	v_cvt_pk_bf16_f32 v103, v92, v93
	global_store_dwordx4 v[110:111], v[94:97], off
	global_store_dwordx4 v[110:111], v[90:93], off offset:16
	global_store_dwordx4 v[112:113], v[100:103], off
	global_load_dwordx4 v[100:103], v[110:111], off offset:512
	s_nop 0
	global_load_dwordx4 v[104:107], v[110:111], off offset:528
	v_pk_mul_f32 v[90:91], v[90:91], v[90:91]
	v_pk_mul_f32 v[92:93], v[92:93], v[92:93]
	v_pk_fma_f32 v[90:91], v[94:95], v[94:95], v[90:91]
	v_pk_fma_f32 v[92:93], v[96:97], v[96:97], v[92:93]
	v_add_f32_e32 v90, v90, v91
	v_add_f32_e32 v90, v92, v90
	v_add_f32_e32 v94, v93, v90
	s_waitcnt vmcnt(1)
	v_pk_add_f32 v[86:87], v[86:87], v[100:101]
	s_waitcnt vmcnt(0)
	v_pk_add_f32 v[90:91], v[82:83], v[104:105]
	v_pk_add_f32 v[92:93], v[84:85], v[106:107]
	v_pk_mul_f32 v[84:85], v[90:91], v[90:91]
	v_pk_add_f32 v[88:89], v[88:89], v[102:103]
	v_pk_fma_f32 v[84:85], v[86:87], v[86:87], v[84:85]
	v_pk_mul_f32 v[82:83], v[92:93], v[92:93]
	v_add_f32_e32 v84, v94, v84
	v_pk_fma_f32 v[82:83], v[88:89], v[88:89], v[82:83]
	v_add_f32_e32 v84, v85, v84
	v_add_f32_e32 v82, v82, v84
	v_add_f32_e32 v82, v83, v82
	v_mov_b32_e32 v83, v82
	s_nop 1
	v_permlane16_swap_b32_e32 v82, v83
	global_store_dwordx4 v[110:111], v[86:89], off offset:512
	v_lshl_add_u64 v[94:95], s[64:65], 0, v[108:109]
	v_cvt_pk_bf16_f32 v84, v86, v87
	v_cvt_pk_bf16_f32 v85, v88, v89
	s_waitcnt lgkmcnt(0)
	v_add_f32_e32 v82, v82, v83
	v_mov_b32_e32 v83, v82
	s_nop 1
	v_permlane32_swap_b32_e32 v82, v83
	v_cvt_pk_bf16_f32 v86, v90, v91
	v_cvt_pk_bf16_f32 v87, v92, v93
	global_store_dwordx4 v[110:111], v[90:93], off offset:528
	global_store_dwordx4 v[94:95], v[84:87], off
	s_and_saveexec_b64 s[26:27], s[2:3]
	s_cbranch_execz .LBB0_3682
	v_lshl_add_u64 v[84:85], v[98:99], 2, s[12:13]
	s_waitcnt lgkmcnt(0)
	v_add_f32_e32 v82, v82, v83
	global_atomic_add_f32 v[84:85], v82, off
.LBB0_3682:
	s_or_b64 exec, exec, s[26:27]
	v_or_b32_e32 v82, 48, v148
	s_waitcnt lgkmcnt(0)
	v_ashrrev_i32_e32 v83, 31, v82
	v_lshlrev_b64 v[84:85], 10, v[82:83]
	v_lshl_add_u64 v[92:93], v[84:85], 0, v[146:147]
	v_lshl_add_u64 v[94:95], v[92:93], 2, s[8:9]
	global_load_dwordx4 v[84:87], v[94:95], off
	global_load_dwordx4 v[88:91], v[94:95], off offset:16
	v_lshlrev_b64 v[92:93], 1, v[92:93]
	v_lshl_add_u64 v[96:97], s[64:65], 0, v[92:93]
	v_or_b32_e32 v92, 0x100, v92
	s_waitcnt vmcnt(1)
	v_pk_add_f32 v[80:81], v[80:81], v[86:87]
	v_pk_add_f32 v[78:79], v[78:79], v[84:85]
	s_waitcnt vmcnt(0)
	v_pk_add_f32 v[76:77], v[76:77], v[90:91]
	v_pk_add_f32 v[74:75], v[74:75], v[88:89]
	v_cvt_pk_bf16_f32 v84, v78, v79
	v_cvt_pk_bf16_f32 v85, v80, v81
	v_cvt_pk_bf16_f32 v86, v74, v75
	v_cvt_pk_bf16_f32 v87, v76, v77
	global_store_dwordx4 v[94:95], v[78:81], off
	global_store_dwordx4 v[94:95], v[74:77], off offset:16
	global_store_dwordx4 v[96:97], v[84:87], off
	global_load_dwordx4 v[84:87], v[94:95], off offset:512
	s_nop 0
	global_load_dwordx4 v[88:91], v[94:95], off offset:528
	v_pk_mul_f32 v[74:75], v[74:75], v[74:75]
	v_pk_mul_f32 v[76:77], v[76:77], v[76:77]
	v_pk_fma_f32 v[74:75], v[78:79], v[78:79], v[74:75]
	v_pk_fma_f32 v[76:77], v[80:81], v[80:81], v[76:77]
	v_add_f32_e32 v74, v74, v75
	v_add_f32_e32 v74, v76, v74
	v_add_f32_e32 v78, v77, v74
	s_waitcnt vmcnt(1)
	v_pk_add_f32 v[70:71], v[70:71], v[84:85]
	s_waitcnt vmcnt(0)
	v_pk_add_f32 v[74:75], v[66:67], v[88:89]
	v_pk_add_f32 v[76:77], v[68:69], v[90:91]
	v_pk_mul_f32 v[68:69], v[74:75], v[74:75]
	v_pk_add_f32 v[72:73], v[72:73], v[86:87]
	v_pk_fma_f32 v[68:69], v[70:71], v[70:71], v[68:69]
	v_pk_mul_f32 v[66:67], v[76:77], v[76:77]
	v_add_f32_e32 v68, v78, v68
	v_pk_fma_f32 v[66:67], v[72:73], v[72:73], v[66:67]
	v_add_f32_e32 v68, v69, v68
	v_add_f32_e32 v66, v66, v68
	v_add_f32_e32 v66, v67, v66
	v_mov_b32_e32 v67, v66
	s_nop 1
	v_permlane16_swap_b32_e32 v66, v67
	global_store_dwordx4 v[94:95], v[70:73], off offset:512
	v_lshl_add_u64 v[78:79], s[64:65], 0, v[92:93]
	v_cvt_pk_bf16_f32 v68, v70, v71
	v_cvt_pk_bf16_f32 v69, v72, v73
	s_waitcnt lgkmcnt(0)
	v_add_f32_e32 v66, v66, v67
	v_mov_b32_e32 v67, v66
	s_nop 1
	v_permlane32_swap_b32_e32 v66, v67
	v_cvt_pk_bf16_f32 v70, v74, v75
	v_cvt_pk_bf16_f32 v71, v76, v77
	global_store_dwordx4 v[94:95], v[74:77], off offset:528
	global_store_dwordx4 v[78:79], v[68:71], off
	s_and_saveexec_b64 s[26:27], s[2:3]
	s_cbranch_execz .LBB0_3684
	v_lshl_add_u64 v[68:69], v[82:83], 2, s[12:13]
	s_waitcnt lgkmcnt(0)
	v_add_f32_e32 v66, v66, v67
	global_atomic_add_f32 v[68:69], v66, off
; DI unsigned pk_bf16(float a, float b) { f32x2 v = {a, b}; bf2_t r = __builtin_convertvector(v, bf2_t); return __builtin_bit_cast(unsigned, r); }
;     DI void operator()(const pg8::f32x4 (&acc)[2][2][4][2], const pg8::Unit& u, int wr, int wc, int fr, int fq) const {
;     ...
;             for (int m = 0; m < 4; ++m) {
;                 const int row = row0 + ai * 128 + m * 16; float ss = 0.f;
;                 const float r2 = sumsq_in ? 1.0f / (sumsq_in[row] * (1.0f / 1024.0f) + EPS) : 1.0f;
; #pragma unroll
;                 for (int bj = 0; bj < 2; ++bj) {
;                     const size_t off = (size_t)row * 1024 + col0 + bj * 128;
;                     f32x4 r0 = *(const f32x4*)(resid + off), r1 = *(const f32x4*)(resid + off + 4);
; #pragma unroll
;                     for (int e = 0; e < 4; ++e) { r0[e] += acc[ai][bj][m][0][e] * r2; r1[e] += acc[ai][bj][m][1][e] * r2; ss += r0[e] * r0[e] + r1[e] * r1[e]; }
;                     *(f32x4*)(hout + off) = r0; *(f32x4*)(hout + off + 4) = r1;
;                     u32x4 w; w.x = pk_bf16(r0[0], r0[1]); w.y = pk_bf16(r0[2], r0[3]); w.z = pk_bf16(r1[0], r1[1]); w.w = pk_bf16(r1[2], r1[3]);
;                     if (hb) *(u32x4*)(hb + off) = w;
;                 }
;                 ss += __shfl_xor(ss, 16); ss += __shfl_xor(ss, 32);
;                 if (fq == 0) __hip_atomic_fetch_add(sumsq_next + row, ss, __ATOMIC_RELAXED, __HIP_MEMORY_SCOPE_AGENT);
;                 asm volatile("" ::: "memory");
;             }
.LBB0_3684:
	s_or_b64 exec, exec, s[26:27]
	v_add_u32_e32 v66, 0x80, v148
	s_waitcnt lgkmcnt(0)
	v_ashrrev_i32_e32 v67, 31, v66
	v_lshlrev_b64 v[68:69], 10, v[66:67]
	v_lshl_add_u64 v[76:77], v[68:69], 0, v[146:147]
	v_lshl_add_u64 v[78:79], v[76:77], 2, s[8:9]
	global_load_dwordx4 v[68:71], v[78:79], off
	global_load_dwordx4 v[72:75], v[78:79], off offset:16
	v_lshlrev_b64 v[76:77], 1, v[76:77]
	v_lshl_add_u64 v[80:81], s[64:65], 0, v[76:77]
	v_or_b32_e32 v76, 0x100, v76
	s_waitcnt vmcnt(1)
	v_pk_add_f32 v[64:65], v[64:65], v[70:71]
	v_pk_add_f32 v[62:63], v[62:63], v[68:69]
	s_waitcnt vmcnt(0)
	v_pk_add_f32 v[60:61], v[60:61], v[74:75]
	v_pk_add_f32 v[58:59], v[58:59], v[72:73]
	v_cvt_pk_bf16_f32 v68, v62, v63
	v_cvt_pk_bf16_f32 v69, v64, v65
	v_cvt_pk_bf16_f32 v70, v58, v59
	v_cvt_pk_bf16_f32 v71, v60, v61
	global_store_dwordx4 v[78:79], v[62:65], off
	global_store_dwordx4 v[78:79], v[58:61], off offset:16
	global_store_dwordx4 v[80:81], v[68:71], off
	global_load_dwordx4 v[68:71], v[78:79], off offset:512
	s_nop 0
	global_load_dwordx4 v[72:75], v[78:79], off offset:528
	v_pk_mul_f32 v[58:59], v[58:59], v[58:59]
	v_pk_mul_f32 v[60:61], v[60:61], v[60:61]
	v_pk_fma_f32 v[58:59], v[62:63], v[62:63], v[58:59]
	v_pk_fma_f32 v[60:61], v[64:65], v[64:65], v[60:61]
	v_add_f32_e32 v58, v58, v59
	v_add_f32_e32 v58, v60, v58
	v_add_f32_e32 v62, v61, v58
	s_waitcnt vmcnt(1)
	v_pk_add_f32 v[54:55], v[54:55], v[68:69]
	s_waitcnt vmcnt(0)
	v_pk_add_f32 v[58:59], v[50:51], v[72:73]
	v_pk_add_f32 v[60:61], v[52:53], v[74:75]
	v_pk_mul_f32 v[52:53], v[58:59], v[58:59]
	v_pk_add_f32 v[56:57], v[56:57], v[70:71]
	v_pk_fma_f32 v[52:53], v[54:55], v[54:55], v[52:53]
	v_pk_mul_f32 v[50:51], v[60:61], v[60:61]
	v_add_f32_e32 v52, v62, v52
	v_pk_fma_f32 v[50:51], v[56:57], v[56:57], v[50:51]
	v_add_f32_e32 v52, v53, v52
	v_add_f32_e32 v50, v50, v52
	v_add_f32_e32 v50, v51, v50
	v_mov_b32_e32 v51, v50
	s_nop 1
	v_permlane16_swap_b32_e32 v50, v51
	global_store_dwordx4 v[78:79], v[54:57], off offset:512
	v_lshl_add_u64 v[62:63], s[64:65], 0, v[76:77]
	v_cvt_pk_bf16_f32 v52, v54, v55
	v_cvt_pk_bf16_f32 v53, v56, v57
	s_waitcnt lgkmcnt(0)
	v_add_f32_e32 v50, v50, v51
	v_mov_b32_e32 v51, v50
	s_nop 1
	v_permlane32_swap_b32_e32 v50, v51
	v_cvt_pk_bf16_f32 v54, v58, v59
	v_cvt_pk_bf16_f32 v55, v60, v61
	global_store_dwordx4 v[78:79], v[58:61], off offset:528
	global_store_dwordx4 v[62:63], v[52:55], off
	s_and_saveexec_b64 s[26:27], s[2:3]
	s_cbranch_execz .LBB0_3686
	v_lshl_add_u64 v[52:53], v[66:67], 2, s[12:13]
	s_waitcnt lgkmcnt(0)
	v_add_f32_e32 v50, v50, v51
	global_atomic_add_f32 v[52:53], v50, off
.LBB0_3686:
	s_or_b64 exec, exec, s[26:27]
	v_add_u32_e32 v50, 0x90, v148
	s_waitcnt lgkmcnt(0)
	v_ashrrev_i32_e32 v51, 31, v50
	v_lshlrev_b64 v[52:53], 10, v[50:51]
	v_lshl_add_u64 v[60:61], v[52:53], 0, v[146:147]
	v_lshl_add_u64 v[62:63], v[60:61], 2, s[8:9]
	global_load_dwordx4 v[52:55], v[62:63], off
	global_load_dwordx4 v[56:59], v[62:63], off offset:16
	v_lshlrev_b64 v[60:61], 1, v[60:61]
	v_lshl_add_u64 v[64:65], s[64:65], 0, v[60:61]
	v_or_b32_e32 v60, 0x100, v60
	s_waitcnt vmcnt(1)
	v_pk_add_f32 v[48:49], v[48:49], v[54:55]
	v_pk_add_f32 v[46:47], v[46:47], v[52:53]
	s_waitcnt vmcnt(0)
	v_pk_add_f32 v[44:45], v[44:45], v[58:59]
	v_pk_add_f32 v[42:43], v[42:43], v[56:57]
	v_cvt_pk_bf16_f32 v52, v46, v47
	v_cvt_pk_bf16_f32 v53, v48, v49
	v_cvt_pk_bf16_f32 v54, v42, v43
	v_cvt_pk_bf16_f32 v55, v44, v45
	global_store_dwordx4 v[62:63], v[46:49], off
	global_store_dwordx4 v[62:63], v[42:45], off offset:16
	global_store_dwordx4 v[64:65], v[52:55], off
	global_load_dwordx4 v[52:55], v[62:63], off offset:512
	s_nop 0
	global_load_dwordx4 v[56:59], v[62:63], off offset:528
	v_pk_mul_f32 v[42:43], v[42:43], v[42:43]
	v_pk_mul_f32 v[44:45], v[44:45], v[44:45]
	v_pk_fma_f32 v[42:43], v[46:47], v[46:47], v[42:43]
	v_pk_fma_f32 v[44:45], v[48:49], v[48:49], v[44:45]
	v_add_f32_e32 v42, v42, v43
	v_add_f32_e32 v42, v44, v42
	v_add_f32_e32 v46, v45, v42
	s_waitcnt vmcnt(1)
	v_pk_add_f32 v[38:39], v[38:39], v[52:53]
	s_waitcnt vmcnt(0)
	v_pk_add_f32 v[42:43], v[34:35], v[56:57]
	v_pk_add_f32 v[44:45], v[36:37], v[58:59]
	v_pk_mul_f32 v[36:37], v[42:43], v[42:43]
	v_pk_add_f32 v[40:41], v[40:41], v[54:55]
	v_pk_fma_f32 v[36:37], v[38:39], v[38:39], v[36:37]
	v_pk_mul_f32 v[34:35], v[44:45], v[44:45]
	v_add_f32_e32 v36, v46, v36
	v_pk_fma_f32 v[34:35], v[40:41], v[40:41], v[34:35]
	v_add_f32_e32 v36, v37, v36
	v_add_f32_e32 v34, v34, v36
	v_add_f32_e32 v34, v35, v34
	v_mov_b32_e32 v35, v34
	s_nop 1
	v_permlane16_swap_b32_e32 v34, v35
	global_store_dwordx4 v[62:63], v[38:41], off offset:512
	v_lshl_add_u64 v[46:47], s[64:65], 0, v[60:61]
	v_cvt_pk_bf16_f32 v36, v38, v39
	v_cvt_pk_bf16_f32 v37, v40, v41
	s_waitcnt lgkmcnt(0)
	v_add_f32_e32 v34, v34, v35
	v_mov_b32_e32 v35, v34
	s_nop 1
	v_permlane32_swap_b32_e32 v34, v35
	v_cvt_pk_bf16_f32 v38, v42, v43
	v_cvt_pk_bf16_f32 v39, v44, v45
	global_store_dwordx4 v[62:63], v[42:45], off offset:528
	global_store_dwordx4 v[46:47], v[36:39], off
	s_and_saveexec_b64 s[26:27], s[2:3]
	s_cbranch_execz .LBB0_3688
	v_lshl_add_u64 v[36:37], v[50:51], 2, s[12:13]
	s_waitcnt lgkmcnt(0)
	v_add_f32_e32 v34, v34, v35
	global_atomic_add_f32 v[36:37], v34, off
; DI unsigned pk_bf16(float a, float b) { f32x2 v = {a, b}; bf2_t r = __builtin_convertvector(v, bf2_t); return __builtin_bit_cast(unsigned, r); }
;     DI void operator()(const pg8::f32x4 (&acc)[2][2][4][2], const pg8::Unit& u, int wr, int wc, int fr, int fq) const {
;     ...
;             for (int m = 0; m < 4; ++m) {
;                 const int row = row0 + ai * 128 + m * 16; float ss = 0.f;
;                 const float r2 = sumsq_in ? 1.0f / (sumsq_in[row] * (1.0f / 1024.0f) + EPS) : 1.0f;
; #pragma unroll
;                 for (int bj = 0; bj < 2; ++bj) {
;                     const size_t off = (size_t)row * 1024 + col0 + bj * 128;
;                     f32x4 r0 = *(const f32x4*)(resid + off), r1 = *(const f32x4*)(resid + off + 4);
; #pragma unroll
;                     for (int e = 0; e < 4; ++e) { r0[e] += acc[ai][bj][m][0][e] * r2; r1[e] += acc[ai][bj][m][1][e] * r2; ss += r0[e] * r0[e] + r1[e] * r1[e]; }
;                     *(f32x4*)(hout + off) = r0; *(f32x4*)(hout + off + 4) = r1;
;                     u32x4 w; w.x = pk_bf16(r0[0], r0[1]); w.y = pk_bf16(r0[2], r0[3]); w.z = pk_bf16(r1[0], r1[1]); w.w = pk_bf16(r1[2], r1[3]);
;                     if (hb) *(u32x4*)(hb + off) = w;
;                 }
;                 ss += __shfl_xor(ss, 16); ss += __shfl_xor(ss, 32);
;                 if (fq == 0) __hip_atomic_fetch_add(sumsq_next + row, ss, __ATOMIC_RELAXED, __HIP_MEMORY_SCOPE_AGENT);
;                 asm volatile("" ::: "memory");
;             }
.LBB0_3688:
	s_or_b64 exec, exec, s[26:27]
	v_add_u32_e32 v34, 0xa0, v148
	s_waitcnt lgkmcnt(0)
	v_ashrrev_i32_e32 v35, 31, v34
	v_lshlrev_b64 v[36:37], 10, v[34:35]
	v_lshl_add_u64 v[44:45], v[36:37], 0, v[146:147]
	v_lshl_add_u64 v[46:47], v[44:45], 2, s[8:9]
	global_load_dwordx4 v[36:39], v[46:47], off
	global_load_dwordx4 v[40:43], v[46:47], off offset:16
	v_lshlrev_b64 v[44:45], 1, v[44:45]
	v_lshl_add_u64 v[48:49], s[64:65], 0, v[44:45]
	v_or_b32_e32 v44, 0x100, v44
	s_waitcnt vmcnt(1)
	v_pk_add_f32 v[32:33], v[32:33], v[38:39]
	v_pk_add_f32 v[30:31], v[30:31], v[36:37]
	s_waitcnt vmcnt(0)
	v_pk_add_f32 v[28:29], v[28:29], v[42:43]
	v_pk_add_f32 v[26:27], v[26:27], v[40:41]
	v_cvt_pk_bf16_f32 v36, v30, v31
	v_cvt_pk_bf16_f32 v37, v32, v33
	v_cvt_pk_bf16_f32 v38, v26, v27
	v_cvt_pk_bf16_f32 v39, v28, v29
	global_store_dwordx4 v[46:47], v[30:33], off
	global_store_dwordx4 v[46:47], v[26:29], off offset:16
	global_store_dwordx4 v[48:49], v[36:39], off
	global_load_dwordx4 v[36:39], v[46:47], off offset:512
	s_nop 0
	global_load_dwordx4 v[40:43], v[46:47], off offset:528
	v_pk_mul_f32 v[26:27], v[26:27], v[26:27]
	v_pk_mul_f32 v[28:29], v[28:29], v[28:29]
	v_pk_fma_f32 v[26:27], v[30:31], v[30:31], v[26:27]
	v_pk_fma_f32 v[28:29], v[32:33], v[32:33], v[28:29]
	v_add_f32_e32 v26, v26, v27
	v_add_f32_e32 v26, v28, v26
	v_add_f32_e32 v30, v29, v26
	s_waitcnt vmcnt(1)
	v_pk_add_f32 v[22:23], v[22:23], v[36:37]
	s_waitcnt vmcnt(0)
	v_pk_add_f32 v[26:27], v[18:19], v[40:41]
	v_pk_add_f32 v[28:29], v[20:21], v[42:43]
	v_pk_mul_f32 v[20:21], v[26:27], v[26:27]
	v_pk_add_f32 v[24:25], v[24:25], v[38:39]
	v_pk_fma_f32 v[20:21], v[22:23], v[22:23], v[20:21]
	v_pk_mul_f32 v[18:19], v[28:29], v[28:29]
	v_add_f32_e32 v20, v30, v20
	v_pk_fma_f32 v[18:19], v[24:25], v[24:25], v[18:19]
	v_add_f32_e32 v20, v21, v20
	v_add_f32_e32 v18, v18, v20
	v_add_f32_e32 v18, v19, v18
	v_mov_b32_e32 v19, v18
	s_nop 1
	v_permlane16_swap_b32_e32 v18, v19
	global_store_dwordx4 v[46:47], v[22:25], off offset:512
	v_lshl_add_u64 v[30:31], s[64:65], 0, v[44:45]
	v_cvt_pk_bf16_f32 v20, v22, v23
	v_cvt_pk_bf16_f32 v21, v24, v25
	s_waitcnt lgkmcnt(0)
	v_add_f32_e32 v18, v18, v19
	v_mov_b32_e32 v19, v18
	s_nop 1
	v_permlane32_swap_b32_e32 v18, v19
	v_cvt_pk_bf16_f32 v22, v26, v27
	v_cvt_pk_bf16_f32 v23, v28, v29
	global_store_dwordx4 v[46:47], v[26:29], off offset:528
	global_store_dwordx4 v[30:31], v[20:23], off
	s_and_saveexec_b64 s[26:27], s[2:3]
	s_cbranch_execz .LBB0_3690
	v_lshl_add_u64 v[20:21], v[34:35], 2, s[12:13]
	s_waitcnt lgkmcnt(0)
	v_add_f32_e32 v18, v18, v19
	global_atomic_add_f32 v[20:21], v18, off
.LBB0_3690:
	s_or_b64 exec, exec, s[26:27]
	v_add_u32_e32 v18, 0xb0, v148
	s_waitcnt lgkmcnt(0)
	v_ashrrev_i32_e32 v19, 31, v18
	v_lshlrev_b64 v[20:21], 10, v[18:19]
	v_lshl_add_u64 v[28:29], v[20:21], 0, v[146:147]
	v_lshl_add_u64 v[30:31], v[28:29], 2, s[8:9]
	global_load_dwordx4 v[20:23], v[30:31], off
	global_load_dwordx4 v[24:27], v[30:31], off offset:16
	v_lshlrev_b64 v[28:29], 1, v[28:29]
	v_lshl_add_u64 v[32:33], s[64:65], 0, v[28:29]
	v_or_b32_e32 v28, 0x100, v28
	s_waitcnt vmcnt(1)
	v_pk_add_f32 v[16:17], v[16:17], v[22:23]
	v_pk_add_f32 v[14:15], v[14:15], v[20:21]
	s_waitcnt vmcnt(0)
	v_pk_add_f32 v[12:13], v[12:13], v[26:27]
	v_pk_add_f32 v[10:11], v[10:11], v[24:25]
	v_cvt_pk_bf16_f32 v20, v14, v15
	v_cvt_pk_bf16_f32 v21, v16, v17
	v_cvt_pk_bf16_f32 v22, v10, v11
	v_cvt_pk_bf16_f32 v23, v12, v13
	global_store_dwordx4 v[30:31], v[14:17], off
	global_store_dwordx4 v[30:31], v[10:13], off offset:16
	global_store_dwordx4 v[32:33], v[20:23], off
	global_load_dwordx4 v[20:23], v[30:31], off offset:512
	s_nop 0
	global_load_dwordx4 v[24:27], v[30:31], off offset:528
	v_pk_mul_f32 v[10:11], v[10:11], v[10:11]
	v_pk_mul_f32 v[12:13], v[12:13], v[12:13]
	v_pk_fma_f32 v[10:11], v[14:15], v[14:15], v[10:11]
	v_pk_fma_f32 v[12:13], v[16:17], v[16:17], v[12:13]
	v_add_f32_e32 v10, v10, v11
	v_add_f32_e32 v10, v12, v10
	v_add_f32_e32 v14, v13, v10
	s_waitcnt vmcnt(1)
	v_pk_add_f32 v[6:7], v[6:7], v[20:21]
	s_waitcnt vmcnt(0)
	v_pk_add_f32 v[10:11], v[2:3], v[24:25]
	v_pk_add_f32 v[12:13], v[4:5], v[26:27]
	v_pk_mul_f32 v[4:5], v[10:11], v[10:11]
	v_pk_add_f32 v[8:9], v[8:9], v[22:23]
	v_pk_fma_f32 v[4:5], v[6:7], v[6:7], v[4:5]
	v_pk_mul_f32 v[2:3], v[12:13], v[12:13]
	v_add_f32_e32 v4, v14, v4
	v_pk_fma_f32 v[2:3], v[8:9], v[8:9], v[2:3]
	v_add_f32_e32 v4, v5, v4
	v_add_f32_e32 v2, v2, v4
	v_add_f32_e32 v2, v3, v2
	v_mov_b32_e32 v3, v2
	s_nop 1
	v_permlane16_swap_b32_e32 v2, v3
	global_store_dwordx4 v[30:31], v[6:9], off offset:512
	v_lshl_add_u64 v[14:15], s[64:65], 0, v[28:29]
	v_cvt_pk_bf16_f32 v4, v6, v7
	v_cvt_pk_bf16_f32 v5, v8, v9
	s_waitcnt lgkmcnt(0)
	v_add_f32_e32 v2, v2, v3
	v_mov_b32_e32 v3, v2
	s_nop 1
	v_permlane32_swap_b32_e32 v2, v3
	v_cvt_pk_bf16_f32 v6, v10, v11
	v_cvt_pk_bf16_f32 v7, v12, v13
	global_store_dwordx4 v[30:31], v[10:13], off offset:528
	global_store_dwordx4 v[14:15], v[4:7], off
	s_and_saveexec_b64 s[26:27], s[2:3]
	s_cbranch_execz .LBB0_3692
	v_lshl_add_u64 v[4:5], v[18:19], 2, s[12:13]
	s_waitcnt lgkmcnt(0)
	v_add_f32_e32 v2, v2, v3
	global_atomic_add_f32 v[4:5], v2, off

; DI unsigned pk_bf16(float a, float b) { f32x2 v = {a, b}; bf2_t r = __builtin_convertvector(v, bf2_t); return __builtin_bit_cast(unsigned, r); }
;     DI void operator()(const pg8::f32x4 (&acc)[2][2][4][2], const pg8::Unit& u, int wr, int wc, int fr, int fq) const {
;     ...
;             for (int m = 0; m < 4; ++m) {
;                 const int row = row0 + ai * 128 + m * 16; float ss = 0.f;
;                 const float r2 = sumsq_in ? 1.0f / (sumsq_in[row] * (1.0f / 1024.0f) + EPS) : 1.0f;
; #pragma unroll
;                 for (int bj = 0; bj < 2; ++bj) {
;                     const size_t off = (size_t)row * 1024 + col0 + bj * 128;
;                     f32x4 r0 = *(const f32x4*)(resid + off), r1 = *(const f32x4*)(resid + off + 4);
; #pragma unroll
;                     for (int e = 0; e < 4; ++e) { r0[e] += acc[ai][bj][m][0][e] * r2; r1[e] += acc[ai][bj][m][1][e] * r2; ss += r0[e] * r0[e] + r1[e] * r1[e]; }
;                     *(f32x4*)(hout + off) = r0; *(f32x4*)(hout + off + 4) = r1;
;                     u32x4 w; w.x = pk_bf16(r0[0], r0[1]); w.y = pk_bf16(r0[2], r0[3]); w.z = pk_bf16(r1[0], r1[1]); w.w = pk_bf16(r1[2], r1[3]);
;                     if (hb) *(u32x4*)(hb + off) = w;
;                 }
;                 ss += __shfl_xor(ss, 16); ss += __shfl_xor(ss, 32);
;                 if (fq == 0) __hip_atomic_fetch_add(sumsq_next + row, ss, __ATOMIC_RELAXED, __HIP_MEMORY_SCOPE_AGENT);
;                 asm volatile("" ::: "memory");
;             }
.LBB0_3762:
	v_lshl_add_u32 v146, s30, 8, v1
	v_ashrrev_i32_e32 v147, 31, v146
	v_lshl_add_u64 v[150:151], v[146:147], 2, s[14:15]
	global_load_dword v159, v[150:151], off
	v_lshl_or_b32 v148, s28, 8, v153
	v_lshlrev_b64 v[160:161], 12, v[146:147]
	v_ashrrev_i32_e32 v149, 31, v148
	v_lshl_add_u64 v[160:161], s[8:9], 0, v[160:161]
	v_lshl_add_u64 v[176:177], v[148:149], 2, v[160:161]
	global_load_dwordx4 v[160:163], v[176:177], off
	global_load_dwordx4 v[164:167], v[176:177], off offset:16
	global_load_dwordx4 v[168:171], v[176:177], off offset:512
	global_load_dwordx4 v[172:175], v[176:177], off offset:528
	v_and_b32_e32 v179, 64, v157
	v_xor_b32_e32 v178, 16, v157
	v_add_u32_e32 v179, 64, v179
	v_cmp_lt_i32_e32 vcc, v178, v179
	s_waitcnt vmcnt(0)
	v_fmamk_f32 v180, v159, 0x3a800000, v158
	v_div_scale_f32 v181, s[0:1], v180, v180, 1.0
	v_rcp_f32_e32 v182, v181
	v_cndmask_b32_e32 v178, v157, v178, vcc
	v_lshlrev_b32_e32 v159, 2, v178
	v_div_scale_f32 v178, vcc, 1.0, v180, 1.0
	v_fma_f32 v183, -v181, v182, 1.0
	v_fmac_f32_e32 v182, v183, v182
	v_mul_f32_e32 v183, v178, v182
	v_fma_f32 v184, -v181, v183, v178
	v_fmac_f32_e32 v183, v184, v182
	v_fma_f32 v178, -v181, v183, v178
	v_div_fmas_f32 v178, v178, v182, v183
	v_div_fixup_f32 v178, v178, v180, 1.0
	v_pk_fma_f32 v[122:123], v[122:123], v[178:179], v[164:165] op_sel_hi:[1,0,1]
	v_pk_fma_f32 v[126:127], v[126:127], v[178:179], v[160:161] op_sel_hi:[1,0,1]
	v_pk_fma_f32 v[124:125], v[124:125], v[178:179], v[166:167] op_sel_hi:[1,0,1]
	v_pk_fma_f32 v[160:161], v[114:115], v[178:179], v[172:173] op_sel_hi:[1,0,1]
	v_pk_mul_f32 v[114:115], v[122:123], v[122:123]
	v_pk_fma_f32 v[128:129], v[128:129], v[178:179], v[162:163] op_sel_hi:[1,0,1]
	v_pk_fma_f32 v[162:163], v[116:117], v[178:179], v[174:175] op_sel_hi:[1,0,1]
	v_pk_mul_f32 v[116:117], v[124:125], v[124:125]
	v_pk_fma_f32 v[114:115], v[126:127], v[126:127], v[114:115]
	v_pk_fma_f32 v[116:117], v[128:129], v[128:129], v[116:117]
	v_add_f32_e32 v114, v114, v115
	v_pk_fma_f32 v[118:119], v[118:119], v[178:179], v[168:169] op_sel_hi:[1,0,1]
	v_pk_mul_f32 v[164:165], v[160:161], v[160:161]
	v_add_f32_e32 v114, v116, v114
	v_pk_fma_f32 v[164:165], v[118:119], v[118:119], v[164:165]
	v_add_f32_e32 v114, v117, v114
	v_pk_fma_f32 v[120:121], v[120:121], v[178:179], v[170:171] op_sel_hi:[1,0,1]
	v_pk_mul_f32 v[166:167], v[162:163], v[162:163]
	v_add_f32_e32 v114, v114, v164
	v_pk_fma_f32 v[166:167], v[120:121], v[120:121], v[166:167]
	v_add_f32_e32 v114, v165, v114
	v_add_f32_e32 v114, v166, v114
	v_add_f32_e32 v114, v167, v114
	v_mov_b32_e32 v115, v114
	s_nop 1
	v_permlane16_swap_b32_e32 v114, v115
	v_xor_b32_e32 v116, 32, v157
	v_cmp_lt_i32_e32 vcc, v116, v179
	global_store_dwordx4 v[176:177], v[126:129], off
	global_store_dwordx4 v[176:177], v[122:125], off offset:16
	global_store_dwordx4 v[176:177], v[118:121], off offset:512
	global_store_dwordx4 v[176:177], v[160:163], off offset:528
	v_cndmask_b32_e32 v116, v157, v116, vcc
	v_lshlrev_b32_e32 v116, 2, v116
	s_waitcnt lgkmcnt(0)
	v_add_f32_e32 v114, v114, v115
	v_mov_b32_e32 v115, v114
	s_nop 1
	v_permlane32_swap_b32_e32 v114, v115
	s_and_saveexec_b64 s[28:29], s[2:3]
	s_cbranch_execz .LBB0_3764
	v_lshl_add_u64 v[118:119], v[146:147], 2, s[12:13]
	s_waitcnt lgkmcnt(0)
	v_add_f32_e32 v114, v114, v115
	global_atomic_add_f32 v[118:119], v114, off
.LBB0_3764:
	s_or_b64 exec, exec, s[28:29]
	v_or_b32_e32 v114, 16, v146
	s_waitcnt lgkmcnt(0)
	v_ashrrev_i32_e32 v115, 31, v114
	v_lshl_add_u64 v[118:119], v[114:115], 2, s[14:15]
	global_load_dword v117, v[118:119], off
	v_lshlrev_b64 v[118:119], 12, v[114:115]
	v_lshl_add_u64 v[118:119], s[8:9], 0, v[118:119]
	v_lshl_add_u64 v[164:165], v[148:149], 2, v[118:119]
	global_load_dwordx4 v[118:121], v[164:165], off
	global_load_dwordx4 v[122:125], v[164:165], off offset:16
	global_load_dwordx4 v[126:129], v[164:165], off offset:512
	global_load_dwordx4 v[160:163], v[164:165], off offset:528
	s_waitcnt vmcnt(4)
	v_fmamk_f32 v117, v117, 0x3a800000, v158
	v_div_scale_f32 v147, s[0:1], v117, v117, 1.0
	v_rcp_f32_e32 v166, v147
	v_div_scale_f32 v167, vcc, 1.0, v117, 1.0
	v_fma_f32 v168, -v147, v166, 1.0
	v_fmac_f32_e32 v166, v168, v166
	v_mul_f32_e32 v168, v167, v166
	v_fma_f32 v169, -v147, v168, v167
	v_fmac_f32_e32 v168, v169, v166
	v_fma_f32 v147, -v147, v168, v167
	v_div_fmas_f32 v147, v147, v166, v168
	v_div_fixup_f32 v166, v147, v117, 1.0
	s_waitcnt vmcnt(2)
	v_pk_fma_f32 v[106:107], v[106:107], v[166:167], v[122:123] op_sel_hi:[1,0,1]
	v_pk_fma_f32 v[110:111], v[110:111], v[166:167], v[118:119] op_sel_hi:[1,0,1]
	v_pk_fma_f32 v[108:109], v[108:109], v[166:167], v[124:125] op_sel_hi:[1,0,1]
	s_waitcnt vmcnt(0)
	v_pk_fma_f32 v[118:119], v[98:99], v[166:167], v[160:161] op_sel_hi:[1,0,1]
	v_pk_mul_f32 v[98:99], v[106:107], v[106:107]
	v_pk_fma_f32 v[112:113], v[112:113], v[166:167], v[120:121] op_sel_hi:[1,0,1]
	v_pk_fma_f32 v[120:121], v[100:101], v[166:167], v[162:163] op_sel_hi:[1,0,1]
	v_pk_mul_f32 v[100:101], v[108:109], v[108:109]
	v_pk_fma_f32 v[98:99], v[110:111], v[110:111], v[98:99]
	v_pk_fma_f32 v[100:101], v[112:113], v[112:113], v[100:101]
	v_add_f32_e32 v98, v98, v99
	v_pk_fma_f32 v[102:103], v[102:103], v[166:167], v[126:127] op_sel_hi:[1,0,1]
	v_pk_mul_f32 v[122:123], v[118:119], v[118:119]
	v_add_f32_e32 v98, v100, v98
	v_pk_fma_f32 v[122:123], v[102:103], v[102:103], v[122:123]
	v_add_f32_e32 v98, v101, v98
	v_pk_fma_f32 v[104:105], v[104:105], v[166:167], v[128:129] op_sel_hi:[1,0,1]
	v_pk_mul_f32 v[124:125], v[120:121], v[120:121]
	v_add_f32_e32 v98, v98, v122
	v_pk_fma_f32 v[124:125], v[104:105], v[104:105], v[124:125]
	v_add_f32_e32 v98, v123, v98
	v_add_f32_e32 v98, v124, v98
	v_add_f32_e32 v98, v125, v98
	v_mov_b32_e32 v99, v98
	s_nop 1
	v_permlane16_swap_b32_e32 v98, v99
	global_store_dwordx4 v[164:165], v[110:113], off
	global_store_dwordx4 v[164:165], v[106:109], off offset:16
	global_store_dwordx4 v[164:165], v[102:105], off offset:512
	global_store_dwordx4 v[164:165], v[118:121], off offset:528
	s_waitcnt lgkmcnt(0)
	v_add_f32_e32 v98, v98, v99
	v_mov_b32_e32 v99, v98
	s_nop 1
	v_permlane32_swap_b32_e32 v98, v99
	s_and_saveexec_b64 s[28:29], s[2:3]
	s_cbranch_execz .LBB0_3766
	v_lshl_add_u64 v[100:101], v[114:115], 2, s[12:13]
	s_waitcnt lgkmcnt(0)
	v_add_f32_e32 v98, v98, v99
	global_atomic_add_f32 v[100:101], v98, off
; DI unsigned pk_bf16(float a, float b) { f32x2 v = {a, b}; bf2_t r = __builtin_convertvector(v, bf2_t); return __builtin_bit_cast(unsigned, r); }
;     DI void operator()(const pg8::f32x4 (&acc)[2][2][4][2], const pg8::Unit& u, int wr, int wc, int fr, int fq) const {
;     ...
;             for (int m = 0; m < 4; ++m) {
;                 const int row = row0 + ai * 128 + m * 16; float ss = 0.f;
;                 const float r2 = sumsq_in ? 1.0f / (sumsq_in[row] * (1.0f / 1024.0f) + EPS) : 1.0f;
; #pragma unroll
;                 for (int bj = 0; bj < 2; ++bj) {
;                     const size_t off = (size_t)row * 1024 + col0 + bj * 128;
;                     f32x4 r0 = *(const f32x4*)(resid + off), r1 = *(const f32x4*)(resid + off + 4);
; #pragma unroll
;                     for (int e = 0; e < 4; ++e) { r0[e] += acc[ai][bj][m][0][e] * r2; r1[e] += acc[ai][bj][m][1][e] * r2; ss += r0[e] * r0[e] + r1[e] * r1[e]; }
;                     *(f32x4*)(hout + off) = r0; *(f32x4*)(hout + off + 4) = r1;
;                     u32x4 w; w.x = pk_bf16(r0[0], r0[1]); w.y = pk_bf16(r0[2], r0[3]); w.z = pk_bf16(r1[0], r1[1]); w.w = pk_bf16(r1[2], r1[3]);
;                     if (hb) *(u32x4*)(hb + off) = w;
;                 }
;                 ss += __shfl_xor(ss, 16); ss += __shfl_xor(ss, 32);
;                 if (fq == 0) __hip_atomic_fetch_add(sumsq_next + row, ss, __ATOMIC_RELAXED, __HIP_MEMORY_SCOPE_AGENT);
;                 asm volatile("" ::: "memory");
;             }
.LBB0_3766:
	s_or_b64 exec, exec, s[28:29]
	v_or_b32_e32 v98, 32, v146
	s_waitcnt lgkmcnt(0)
	v_ashrrev_i32_e32 v99, 31, v98
	v_lshl_add_u64 v[100:101], v[98:99], 2, s[14:15]
	global_load_dword v117, v[100:101], off
	v_lshlrev_b64 v[100:101], 12, v[98:99]
	v_lshl_add_u64 v[100:101], s[8:9], 0, v[100:101]
	v_lshl_add_u64 v[118:119], v[148:149], 2, v[100:101]
	global_load_dwordx4 v[100:103], v[118:119], off
	global_load_dwordx4 v[104:107], v[118:119], off offset:16
	global_load_dwordx4 v[108:111], v[118:119], off offset:512
	global_load_dwordx4 v[112:115], v[118:119], off offset:528
	s_waitcnt vmcnt(4)
	v_fmamk_f32 v117, v117, 0x3a800000, v158
	v_div_scale_f32 v120, s[0:1], v117, v117, 1.0
	v_rcp_f32_e32 v121, v120
	v_div_scale_f32 v122, vcc, 1.0, v117, 1.0
	v_fma_f32 v123, -v120, v121, 1.0
	v_fmac_f32_e32 v121, v123, v121
	v_mul_f32_e32 v123, v122, v121
	v_fma_f32 v124, -v120, v123, v122
	v_fmac_f32_e32 v123, v124, v121
	v_fma_f32 v120, -v120, v123, v122
	v_div_fmas_f32 v120, v120, v121, v123
	v_div_fixup_f32 v120, v120, v117, 1.0
	s_waitcnt vmcnt(2)
	v_pk_fma_f32 v[90:91], v[90:91], v[120:121], v[104:105] op_sel_hi:[1,0,1]
	v_pk_fma_f32 v[94:95], v[94:95], v[120:121], v[100:101] op_sel_hi:[1,0,1]
	v_pk_fma_f32 v[92:93], v[92:93], v[120:121], v[106:107] op_sel_hi:[1,0,1]
	s_waitcnt vmcnt(0)
	v_pk_fma_f32 v[100:101], v[82:83], v[120:121], v[112:113] op_sel_hi:[1,0,1]
	v_pk_mul_f32 v[82:83], v[90:91], v[90:91]
	v_pk_fma_f32 v[96:97], v[96:97], v[120:121], v[102:103] op_sel_hi:[1,0,1]
	v_pk_fma_f32 v[102:103], v[84:85], v[120:121], v[114:115] op_sel_hi:[1,0,1]
	v_pk_mul_f32 v[84:85], v[92:93], v[92:93]
	v_pk_fma_f32 v[82:83], v[94:95], v[94:95], v[82:83]
	v_pk_fma_f32 v[84:85], v[96:97], v[96:97], v[84:85]
	v_add_f32_e32 v82, v82, v83
	v_pk_fma_f32 v[86:87], v[86:87], v[120:121], v[108:109] op_sel_hi:[1,0,1]
	v_pk_mul_f32 v[104:105], v[100:101], v[100:101]
	v_add_f32_e32 v82, v84, v82
	v_pk_fma_f32 v[104:105], v[86:87], v[86:87], v[104:105]
	v_add_f32_e32 v82, v85, v82
	v_pk_fma_f32 v[88:89], v[88:89], v[120:121], v[110:111] op_sel_hi:[1,0,1]
	v_pk_mul_f32 v[106:107], v[102:103], v[102:103]
	v_add_f32_e32 v82, v82, v104
	v_pk_fma_f32 v[106:107], v[88:89], v[88:89], v[106:107]
	v_add_f32_e32 v82, v105, v82
	v_add_f32_e32 v82, v106, v82
	v_add_f32_e32 v82, v107, v82
	v_mov_b32_e32 v83, v82
	s_nop 1
	v_permlane16_swap_b32_e32 v82, v83
	global_store_dwordx4 v[118:119], v[94:97], off
	global_store_dwordx4 v[118:119], v[90:93], off offset:16
	global_store_dwordx4 v[118:119], v[86:89], off offset:512
	global_store_dwordx4 v[118:119], v[100:103], off offset:528
	s_waitcnt lgkmcnt(0)
	v_add_f32_e32 v82, v82, v83
	v_mov_b32_e32 v83, v82
	s_nop 1
	v_permlane32_swap_b32_e32 v82, v83
	s_and_saveexec_b64 s[28:29], s[2:3]
	s_cbranch_execz .LBB0_3768
	v_lshl_add_u64 v[84:85], v[98:99], 2, s[12:13]
	s_waitcnt lgkmcnt(0)
	v_add_f32_e32 v82, v82, v83
	global_atomic_add_f32 v[84:85], v82, off
.LBB0_3768:
	s_or_b64 exec, exec, s[28:29]
	v_or_b32_e32 v82, 48, v146
	s_waitcnt lgkmcnt(0)
	v_ashrrev_i32_e32 v83, 31, v82
	v_lshl_add_u64 v[84:85], v[82:83], 2, s[14:15]
	global_load_dword v102, v[84:85], off
	v_lshlrev_b64 v[84:85], 12, v[82:83]
	v_lshl_add_u64 v[84:85], s[8:9], 0, v[84:85]
	v_lshl_add_u64 v[100:101], v[148:149], 2, v[84:85]
	global_load_dwordx4 v[84:87], v[100:101], off
	global_load_dwordx4 v[88:91], v[100:101], off offset:16
	global_load_dwordx4 v[92:95], v[100:101], off offset:512
	global_load_dwordx4 v[96:99], v[100:101], off offset:528
	s_waitcnt vmcnt(4)
	v_fmamk_f32 v102, v102, 0x3a800000, v158
	v_div_scale_f32 v103, s[0:1], v102, v102, 1.0
	v_rcp_f32_e32 v104, v103
	v_div_scale_f32 v105, vcc, 1.0, v102, 1.0
	v_fma_f32 v106, -v103, v104, 1.0
	v_fmac_f32_e32 v104, v106, v104
	v_mul_f32_e32 v106, v105, v104
	v_fma_f32 v107, -v103, v106, v105
	v_fmac_f32_e32 v106, v107, v104
	v_fma_f32 v103, -v103, v106, v105
	v_div_fmas_f32 v103, v103, v104, v106
	v_div_fixup_f32 v102, v103, v102, 1.0
	s_waitcnt vmcnt(2)
	v_pk_fma_f32 v[74:75], v[74:75], v[102:103], v[88:89] op_sel_hi:[1,0,1]
	v_pk_fma_f32 v[78:79], v[78:79], v[102:103], v[84:85] op_sel_hi:[1,0,1]
	v_pk_fma_f32 v[76:77], v[76:77], v[102:103], v[90:91] op_sel_hi:[1,0,1]
	s_waitcnt vmcnt(0)
	v_pk_fma_f32 v[84:85], v[66:67], v[102:103], v[96:97] op_sel_hi:[1,0,1]
	v_pk_mul_f32 v[66:67], v[74:75], v[74:75]
	v_pk_fma_f32 v[80:81], v[80:81], v[102:103], v[86:87] op_sel_hi:[1,0,1]
	v_pk_fma_f32 v[86:87], v[68:69], v[102:103], v[98:99] op_sel_hi:[1,0,1]
	v_pk_mul_f32 v[68:69], v[76:77], v[76:77]
	v_pk_fma_f32 v[66:67], v[78:79], v[78:79], v[66:67]
	v_pk_fma_f32 v[68:69], v[80:81], v[80:81], v[68:69]
	v_add_f32_e32 v66, v66, v67
	v_pk_fma_f32 v[70:71], v[70:71], v[102:103], v[92:93] op_sel_hi:[1,0,1]
	v_pk_mul_f32 v[88:89], v[84:85], v[84:85]
	v_add_f32_e32 v66, v68, v66
	v_pk_fma_f32 v[88:89], v[70:71], v[70:71], v[88:89]
	v_add_f32_e32 v66, v69, v66
	v_pk_fma_f32 v[72:73], v[72:73], v[102:103], v[94:95] op_sel_hi:[1,0,1]
	v_pk_mul_f32 v[90:91], v[86:87], v[86:87]
	v_add_f32_e32 v66, v66, v88
	v_pk_fma_f32 v[90:91], v[72:73], v[72:73], v[90:91]
	v_add_f32_e32 v66, v89, v66
	v_add_f32_e32 v66, v90, v66
	v_add_f32_e32 v66, v91, v66
	v_mov_b32_e32 v67, v66
	s_nop 1
	v_permlane16_swap_b32_e32 v66, v67
	global_store_dwordx4 v[100:101], v[78:81], off
	global_store_dwordx4 v[100:101], v[74:77], off offset:16
	global_store_dwordx4 v[100:101], v[70:73], off offset:512
	global_store_dwordx4 v[100:101], v[84:87], off offset:528
	s_waitcnt lgkmcnt(0)
	v_add_f32_e32 v66, v66, v67
	v_mov_b32_e32 v67, v66
	s_nop 1
	v_permlane32_swap_b32_e32 v66, v67
	s_and_saveexec_b64 s[28:29], s[2:3]
	s_cbranch_execz .LBB0_3770
	v_lshl_add_u64 v[68:69], v[82:83], 2, s[12:13]
	s_waitcnt lgkmcnt(0)
	v_add_f32_e32 v66, v66, v67
	global_atomic_add_f32 v[68:69], v66, off
; DI unsigned pk_bf16(float a, float b) { f32x2 v = {a, b}; bf2_t r = __builtin_convertvector(v, bf2_t); return __builtin_bit_cast(unsigned, r); }
;     DI void operator()(const pg8::f32x4 (&acc)[2][2][4][2], const pg8::Unit& u, int wr, int wc, int fr, int fq) const {
;     ...
;             for (int m = 0; m < 4; ++m) {
;                 const int row = row0 + ai * 128 + m * 16; float ss = 0.f;
;                 const float r2 = sumsq_in ? 1.0f / (sumsq_in[row] * (1.0f / 1024.0f) + EPS) : 1.0f;
; #pragma unroll
;                 for (int bj = 0; bj < 2; ++bj) {
;                     const size_t off = (size_t)row * 1024 + col0 + bj * 128;
;                     f32x4 r0 = *(const f32x4*)(resid + off), r1 = *(const f32x4*)(resid + off + 4);
; #pragma unroll
;                     for (int e = 0; e < 4; ++e) { r0[e] += acc[ai][bj][m][0][e] * r2; r1[e] += acc[ai][bj][m][1][e] * r2; ss += r0[e] * r0[e] + r1[e] * r1[e]; }
;                     *(f32x4*)(hout + off) = r0; *(f32x4*)(hout + off + 4) = r1;
;                     u32x4 w; w.x = pk_bf16(r0[0], r0[1]); w.y = pk_bf16(r0[2], r0[3]); w.z = pk_bf16(r1[0], r1[1]); w.w = pk_bf16(r1[2], r1[3]);
;                     if (hb) *(u32x4*)(hb + off) = w;
;                 }
;                 ss += __shfl_xor(ss, 16); ss += __shfl_xor(ss, 32);
;                 if (fq == 0) __hip_atomic_fetch_add(sumsq_next + row, ss, __ATOMIC_RELAXED, __HIP_MEMORY_SCOPE_AGENT);
;                 asm volatile("" ::: "memory");
;             }
.LBB0_3770:
	s_or_b64 exec, exec, s[28:29]
	global_load_dword v86, v[150:151], off offset:512
	v_add_u32_e32 v66, 0x80, v146
	s_waitcnt lgkmcnt(0)
	v_ashrrev_i32_e32 v67, 31, v66
	v_lshlrev_b64 v[68:69], 12, v[66:67]
	v_lshl_add_u64 v[68:69], s[8:9], 0, v[68:69]
	v_lshl_add_u64 v[84:85], v[148:149], 2, v[68:69]
	global_load_dwordx4 v[68:71], v[84:85], off
	global_load_dwordx4 v[72:75], v[84:85], off offset:16
	global_load_dwordx4 v[76:79], v[84:85], off offset:512
	global_load_dwordx4 v[80:83], v[84:85], off offset:528
	s_waitcnt vmcnt(4)
	v_fmamk_f32 v86, v86, 0x3a800000, v158
	v_div_scale_f32 v87, s[0:1], v86, v86, 1.0
	v_rcp_f32_e32 v88, v87
	v_div_scale_f32 v89, vcc, 1.0, v86, 1.0
	v_fma_f32 v90, -v87, v88, 1.0
	v_fmac_f32_e32 v88, v90, v88
	v_mul_f32_e32 v90, v89, v88
	v_fma_f32 v91, -v87, v90, v89
	v_fmac_f32_e32 v90, v91, v88
	v_fma_f32 v87, -v87, v90, v89
	v_div_fmas_f32 v87, v87, v88, v90
	v_div_fixup_f32 v86, v87, v86, 1.0
	s_waitcnt vmcnt(2)
	v_pk_fma_f32 v[58:59], v[58:59], v[86:87], v[72:73] op_sel_hi:[1,0,1]
	v_pk_fma_f32 v[62:63], v[62:63], v[86:87], v[68:69] op_sel_hi:[1,0,1]
	v_pk_fma_f32 v[60:61], v[60:61], v[86:87], v[74:75] op_sel_hi:[1,0,1]
	s_waitcnt vmcnt(0)
	v_pk_fma_f32 v[68:69], v[50:51], v[86:87], v[80:81] op_sel_hi:[1,0,1]
	v_pk_mul_f32 v[50:51], v[58:59], v[58:59]
	v_pk_fma_f32 v[64:65], v[64:65], v[86:87], v[70:71] op_sel_hi:[1,0,1]
	v_pk_fma_f32 v[70:71], v[52:53], v[86:87], v[82:83] op_sel_hi:[1,0,1]
	v_pk_mul_f32 v[52:53], v[60:61], v[60:61]
	v_pk_fma_f32 v[50:51], v[62:63], v[62:63], v[50:51]
	v_pk_fma_f32 v[52:53], v[64:65], v[64:65], v[52:53]
	v_add_f32_e32 v50, v50, v51
	v_pk_fma_f32 v[54:55], v[54:55], v[86:87], v[76:77] op_sel_hi:[1,0,1]
	v_pk_mul_f32 v[72:73], v[68:69], v[68:69]
	v_add_f32_e32 v50, v52, v50
	v_pk_fma_f32 v[72:73], v[54:55], v[54:55], v[72:73]
	v_add_f32_e32 v50, v53, v50
	v_pk_fma_f32 v[56:57], v[56:57], v[86:87], v[78:79] op_sel_hi:[1,0,1]
	v_pk_mul_f32 v[74:75], v[70:71], v[70:71]
	v_add_f32_e32 v50, v50, v72
	v_pk_fma_f32 v[74:75], v[56:57], v[56:57], v[74:75]
	v_add_f32_e32 v50, v73, v50
	v_add_f32_e32 v50, v74, v50
	v_add_f32_e32 v50, v75, v50
	v_mov_b32_e32 v51, v50
	s_nop 1
	v_permlane16_swap_b32_e32 v50, v51
	global_store_dwordx4 v[84:85], v[62:65], off
	global_store_dwordx4 v[84:85], v[58:61], off offset:16
	global_store_dwordx4 v[84:85], v[54:57], off offset:512
	global_store_dwordx4 v[84:85], v[68:71], off offset:528
	s_waitcnt lgkmcnt(0)
	v_add_f32_e32 v50, v50, v51
	v_mov_b32_e32 v51, v50
	s_nop 1
	v_permlane32_swap_b32_e32 v50, v51
	s_and_saveexec_b64 s[28:29], s[2:3]
	s_cbranch_execz .LBB0_3772
	v_lshl_add_u64 v[52:53], v[66:67], 2, s[12:13]
	s_waitcnt lgkmcnt(0)
	v_add_f32_e32 v50, v50, v51
	global_atomic_add_f32 v[52:53], v50, off
.LBB0_3772:
	s_or_b64 exec, exec, s[28:29]
	global_load_dword v70, v[150:151], off offset:576
	v_add_u32_e32 v50, 0x90, v146
	s_waitcnt lgkmcnt(0)
	v_ashrrev_i32_e32 v51, 31, v50
	v_lshlrev_b64 v[52:53], 12, v[50:51]
	v_lshl_add_u64 v[52:53], s[8:9], 0, v[52:53]
	v_lshl_add_u64 v[68:69], v[148:149], 2, v[52:53]
	global_load_dwordx4 v[52:55], v[68:69], off
	global_load_dwordx4 v[56:59], v[68:69], off offset:16
	global_load_dwordx4 v[60:63], v[68:69], off offset:512
	global_load_dwordx4 v[64:67], v[68:69], off offset:528
	s_waitcnt vmcnt(4)
	v_fmamk_f32 v70, v70, 0x3a800000, v158
	v_div_scale_f32 v71, s[0:1], v70, v70, 1.0
	v_rcp_f32_e32 v72, v71
	v_div_scale_f32 v73, vcc, 1.0, v70, 1.0
	v_fma_f32 v74, -v71, v72, 1.0
	v_fmac_f32_e32 v72, v74, v72
	v_mul_f32_e32 v74, v73, v72
	v_fma_f32 v75, -v71, v74, v73
	v_fmac_f32_e32 v74, v75, v72
	v_fma_f32 v71, -v71, v74, v73
	v_div_fmas_f32 v71, v71, v72, v74
	v_div_fixup_f32 v70, v71, v70, 1.0
	s_waitcnt vmcnt(2)
	v_pk_fma_f32 v[42:43], v[42:43], v[70:71], v[56:57] op_sel_hi:[1,0,1]
	v_pk_fma_f32 v[46:47], v[46:47], v[70:71], v[52:53] op_sel_hi:[1,0,1]
	v_pk_fma_f32 v[44:45], v[44:45], v[70:71], v[58:59] op_sel_hi:[1,0,1]
	s_waitcnt vmcnt(0)
	v_pk_fma_f32 v[52:53], v[34:35], v[70:71], v[64:65] op_sel_hi:[1,0,1]
	v_pk_mul_f32 v[34:35], v[42:43], v[42:43]
	v_pk_fma_f32 v[48:49], v[48:49], v[70:71], v[54:55] op_sel_hi:[1,0,1]
	v_pk_fma_f32 v[54:55], v[36:37], v[70:71], v[66:67] op_sel_hi:[1,0,1]
	v_pk_mul_f32 v[36:37], v[44:45], v[44:45]
	v_pk_fma_f32 v[34:35], v[46:47], v[46:47], v[34:35]
	v_pk_fma_f32 v[36:37], v[48:49], v[48:49], v[36:37]
	v_add_f32_e32 v34, v34, v35
	v_pk_fma_f32 v[38:39], v[38:39], v[70:71], v[60:61] op_sel_hi:[1,0,1]
	v_pk_mul_f32 v[56:57], v[52:53], v[52:53]
	v_add_f32_e32 v34, v36, v34
	v_pk_fma_f32 v[56:57], v[38:39], v[38:39], v[56:57]
	v_add_f32_e32 v34, v37, v34
	v_pk_fma_f32 v[40:41], v[40:41], v[70:71], v[62:63] op_sel_hi:[1,0,1]
	v_pk_mul_f32 v[58:59], v[54:55], v[54:55]
	v_add_f32_e32 v34, v34, v56
	v_pk_fma_f32 v[58:59], v[40:41], v[40:41], v[58:59]
	v_add_f32_e32 v34, v57, v34
	v_add_f32_e32 v34, v58, v34
	v_add_f32_e32 v34, v59, v34
	v_mov_b32_e32 v35, v34
	s_nop 1
	v_permlane16_swap_b32_e32 v34, v35
	global_store_dwordx4 v[68:69], v[46:49], off
	global_store_dwordx4 v[68:69], v[42:45], off offset:16
	global_store_dwordx4 v[68:69], v[38:41], off offset:512
	global_store_dwordx4 v[68:69], v[52:55], off offset:528
	s_waitcnt lgkmcnt(0)
	v_add_f32_e32 v34, v34, v35
	v_mov_b32_e32 v35, v34
	s_nop 1
	v_permlane32_swap_b32_e32 v34, v35
	s_and_saveexec_b64 s[28:29], s[2:3]
	s_cbranch_execz .LBB0_3774
	v_lshl_add_u64 v[36:37], v[50:51], 2, s[12:13]
	s_waitcnt lgkmcnt(0)
	v_add_f32_e32 v34, v34, v35
	global_atomic_add_f32 v[36:37], v34, off
; DI unsigned pk_bf16(float a, float b) { f32x2 v = {a, b}; bf2_t r = __builtin_convertvector(v, bf2_t); return __builtin_bit_cast(unsigned, r); }
;     DI void operator()(const pg8::f32x4 (&acc)[2][2][4][2], const pg8::Unit& u, int wr, int wc, int fr, int fq) const {
;     ...
;             for (int m = 0; m < 4; ++m) {
;                 const int row = row0 + ai * 128 + m * 16; float ss = 0.f;
;                 const float r2 = sumsq_in ? 1.0f / (sumsq_in[row] * (1.0f / 1024.0f) + EPS) : 1.0f;
; #pragma unroll
;                 for (int bj = 0; bj < 2; ++bj) {
;                     const size_t off = (size_t)row * 1024 + col0 + bj * 128;
;                     f32x4 r0 = *(const f32x4*)(resid + off), r1 = *(const f32x4*)(resid + off + 4);
; #pragma unroll
;                     for (int e = 0; e < 4; ++e) { r0[e] += acc[ai][bj][m][0][e] * r2; r1[e] += acc[ai][bj][m][1][e] * r2; ss += r0[e] * r0[e] + r1[e] * r1[e]; }
;                     *(f32x4*)(hout + off) = r0; *(f32x4*)(hout + off + 4) = r1;
;                     u32x4 w; w.x = pk_bf16(r0[0], r0[1]); w.y = pk_bf16(r0[2], r0[3]); w.z = pk_bf16(r1[0], r1[1]); w.w = pk_bf16(r1[2], r1[3]);
;                     if (hb) *(u32x4*)(hb + off) = w;
;                 }
;                 ss += __shfl_xor(ss, 16); ss += __shfl_xor(ss, 32);
;                 if (fq == 0) __hip_atomic_fetch_add(sumsq_next + row, ss, __ATOMIC_RELAXED, __HIP_MEMORY_SCOPE_AGENT);
;                 asm volatile("" ::: "memory");
;             }
.LBB0_3774:
	s_or_b64 exec, exec, s[28:29]
	global_load_dword v54, v[150:151], off offset:640
	v_add_u32_e32 v34, 0xa0, v146
	s_waitcnt lgkmcnt(0)
	v_ashrrev_i32_e32 v35, 31, v34
	v_lshlrev_b64 v[36:37], 12, v[34:35]
	v_lshl_add_u64 v[36:37], s[8:9], 0, v[36:37]
	v_lshl_add_u64 v[52:53], v[148:149], 2, v[36:37]
	global_load_dwordx4 v[36:39], v[52:53], off
	global_load_dwordx4 v[40:43], v[52:53], off offset:16
	global_load_dwordx4 v[44:47], v[52:53], off offset:512
	global_load_dwordx4 v[48:51], v[52:53], off offset:528
	s_waitcnt vmcnt(4)
	v_fmamk_f32 v54, v54, 0x3a800000, v158
	v_div_scale_f32 v55, s[0:1], v54, v54, 1.0
	v_rcp_f32_e32 v56, v55
	v_div_scale_f32 v57, vcc, 1.0, v54, 1.0
	v_fma_f32 v58, -v55, v56, 1.0
	v_fmac_f32_e32 v56, v58, v56
	v_mul_f32_e32 v58, v57, v56
	v_fma_f32 v59, -v55, v58, v57
	v_fmac_f32_e32 v58, v59, v56
	v_fma_f32 v55, -v55, v58, v57
	v_div_fmas_f32 v55, v55, v56, v58
	v_div_fixup_f32 v54, v55, v54, 1.0
	s_waitcnt vmcnt(2)
	v_pk_fma_f32 v[26:27], v[26:27], v[54:55], v[40:41] op_sel_hi:[1,0,1]
	v_pk_fma_f32 v[30:31], v[30:31], v[54:55], v[36:37] op_sel_hi:[1,0,1]
	v_pk_fma_f32 v[28:29], v[28:29], v[54:55], v[42:43] op_sel_hi:[1,0,1]
	s_waitcnt vmcnt(0)
	v_pk_fma_f32 v[36:37], v[18:19], v[54:55], v[48:49] op_sel_hi:[1,0,1]
	v_pk_mul_f32 v[18:19], v[26:27], v[26:27]
	v_pk_fma_f32 v[32:33], v[32:33], v[54:55], v[38:39] op_sel_hi:[1,0,1]
	v_pk_fma_f32 v[38:39], v[20:21], v[54:55], v[50:51] op_sel_hi:[1,0,1]
	v_pk_mul_f32 v[20:21], v[28:29], v[28:29]
	v_pk_fma_f32 v[18:19], v[30:31], v[30:31], v[18:19]
	v_pk_fma_f32 v[20:21], v[32:33], v[32:33], v[20:21]
	v_add_f32_e32 v18, v18, v19
	v_pk_fma_f32 v[22:23], v[22:23], v[54:55], v[44:45] op_sel_hi:[1,0,1]
	v_pk_mul_f32 v[40:41], v[36:37], v[36:37]
	v_add_f32_e32 v18, v20, v18
	v_pk_fma_f32 v[40:41], v[22:23], v[22:23], v[40:41]
	v_add_f32_e32 v18, v21, v18
	v_pk_fma_f32 v[24:25], v[24:25], v[54:55], v[46:47] op_sel_hi:[1,0,1]
	v_pk_mul_f32 v[42:43], v[38:39], v[38:39]
	v_add_f32_e32 v18, v18, v40
	v_pk_fma_f32 v[42:43], v[24:25], v[24:25], v[42:43]
	v_add_f32_e32 v18, v41, v18
	v_add_f32_e32 v18, v42, v18
	v_add_f32_e32 v18, v43, v18
	v_mov_b32_e32 v19, v18
	s_nop 1
	v_permlane16_swap_b32_e32 v18, v19
	global_store_dwordx4 v[52:53], v[30:33], off
	global_store_dwordx4 v[52:53], v[26:29], off offset:16
	global_store_dwordx4 v[52:53], v[22:25], off offset:512
	global_store_dwordx4 v[52:53], v[36:39], off offset:528
	s_waitcnt lgkmcnt(0)
	v_add_f32_e32 v18, v18, v19
	v_mov_b32_e32 v19, v18
	s_nop 1
	v_permlane32_swap_b32_e32 v18, v19
	s_and_saveexec_b64 s[28:29], s[2:3]
	s_cbranch_execz .LBB0_3776
	v_lshl_add_u64 v[20:21], v[34:35], 2, s[12:13]
	s_waitcnt lgkmcnt(0)
	v_add_f32_e32 v18, v18, v19
	global_atomic_add_f32 v[20:21], v18, off
.LBB0_3776:
	s_or_b64 exec, exec, s[28:29]
	global_load_dword v38, v[150:151], off offset:704
	v_add_u32_e32 v18, 0xb0, v146
	s_waitcnt lgkmcnt(0)
	v_ashrrev_i32_e32 v19, 31, v18
	v_lshlrev_b64 v[20:21], 12, v[18:19]
	v_lshl_add_u64 v[20:21], s[8:9], 0, v[20:21]
	v_lshl_add_u64 v[36:37], v[148:149], 2, v[20:21]
	global_load_dwordx4 v[20:23], v[36:37], off
	global_load_dwordx4 v[24:27], v[36:37], off offset:16
	global_load_dwordx4 v[28:31], v[36:37], off offset:512
	global_load_dwordx4 v[32:35], v[36:37], off offset:528
	s_waitcnt vmcnt(4)
	v_fmamk_f32 v38, v38, 0x3a800000, v158
	v_div_scale_f32 v39, s[0:1], v38, v38, 1.0
	v_rcp_f32_e32 v40, v39
	v_div_scale_f32 v41, vcc, 1.0, v38, 1.0
	v_fma_f32 v42, -v39, v40, 1.0
	v_fmac_f32_e32 v40, v42, v40
	v_mul_f32_e32 v42, v41, v40
	v_fma_f32 v43, -v39, v42, v41
	v_fmac_f32_e32 v42, v43, v40
	v_fma_f32 v39, -v39, v42, v41
	v_div_fmas_f32 v39, v39, v40, v42
	v_div_fixup_f32 v38, v39, v38, 1.0
	s_waitcnt vmcnt(2)
	v_pk_fma_f32 v[10:11], v[10:11], v[38:39], v[24:25] op_sel_hi:[1,0,1]
	v_pk_fma_f32 v[14:15], v[14:15], v[38:39], v[20:21] op_sel_hi:[1,0,1]
	v_pk_fma_f32 v[12:13], v[12:13], v[38:39], v[26:27] op_sel_hi:[1,0,1]
	s_waitcnt vmcnt(0)
	v_pk_fma_f32 v[20:21], v[2:3], v[38:39], v[32:33] op_sel_hi:[1,0,1]
	v_pk_mul_f32 v[2:3], v[10:11], v[10:11]
	v_pk_fma_f32 v[16:17], v[16:17], v[38:39], v[22:23] op_sel_hi:[1,0,1]
	v_pk_fma_f32 v[22:23], v[4:5], v[38:39], v[34:35] op_sel_hi:[1,0,1]
	v_pk_mul_f32 v[4:5], v[12:13], v[12:13]
	v_pk_fma_f32 v[2:3], v[14:15], v[14:15], v[2:3]
	v_pk_fma_f32 v[4:5], v[16:17], v[16:17], v[4:5]
	v_add_f32_e32 v2, v2, v3
	v_pk_fma_f32 v[6:7], v[6:7], v[38:39], v[28:29] op_sel_hi:[1,0,1]
	v_pk_mul_f32 v[24:25], v[20:21], v[20:21]
	v_add_f32_e32 v2, v4, v2
	v_pk_fma_f32 v[24:25], v[6:7], v[6:7], v[24:25]
	v_add_f32_e32 v2, v5, v2
	v_pk_fma_f32 v[8:9], v[8:9], v[38:39], v[30:31] op_sel_hi:[1,0,1]
	v_pk_mul_f32 v[26:27], v[22:23], v[22:23]
	v_add_f32_e32 v2, v2, v24
	v_pk_fma_f32 v[26:27], v[8:9], v[8:9], v[26:27]
	v_add_f32_e32 v2, v25, v2
	v_add_f32_e32 v2, v26, v2
	v_add_f32_e32 v2, v27, v2
	v_mov_b32_e32 v3, v2
	s_nop 1
	v_permlane16_swap_b32_e32 v2, v3
	global_store_dwordx4 v[36:37], v[14:17], off
	global_store_dwordx4 v[36:37], v[10:13], off offset:16
	global_store_dwordx4 v[36:37], v[6:9], off offset:512
	global_store_dwordx4 v[36:37], v[20:23], off offset:528
	s_waitcnt lgkmcnt(0)
	v_add_f32_e32 v2, v2, v3
	v_mov_b32_e32 v3, v2
	s_nop 1
	v_permlane32_swap_b32_e32 v2, v3
	s_and_saveexec_b64 s[28:29], s[2:3]
	s_cbranch_execz .LBB0_3778
	v_lshl_add_u64 v[4:5], v[18:19], 2, s[12:13]
	s_waitcnt lgkmcnt(0)
	v_add_f32_e32 v2, v2, v3
	global_atomic_add_f32 v[4:5], v2, off
